# fox_bounds: loads of each row / key tile issued together (one round trip per row instead of 16), on top of pass2 prefetch
# speedup vs baseline: 1.0298x; 1.0248x over previous
; __device__ __forceinline__ float bflo(unsigned w) { return __uint_as_float(w << 16); }
; __device__ __forceinline__ float bfhi(unsigned w) { return __uint_as_float(w & 0xffff0000u); }
; __device__ __forceinline__ float sq8(const v4u w) { const float a0 = bflo(w.x), a1 = bfhi(w.x), a2 = bflo(w.y), a3 = bfhi(w.y), a4 = bflo(w.z), a5 = bfhi(w.z), a6 = bflo(w.w), a7 = bfhi(w.w); return (a0 * a0 + a1 * a1) + (a2 * a2 + a3 * a3) + (a4 * a4 + a5 * a5) + (a6 * a6 + a7 * a7); }
; __device__ __forceinline__ float dot8(const v4u a, const v4u b) { return (bflo(a.x) * bflo(b.x) + bfhi(a.x) * bfhi(b.x)) + (bflo(a.y) * bflo(b.y) + bfhi(a.y) * bfhi(b.y)) + (bflo(a.z) * bflo(b.z) + bfhi(a.z) * bfhi(b.z)) + (bflo(a.w) * bflo(b.w) + bfhi(a.w) * bfhi(b.w)); }
; __device__ __forceinline__ void fox_bounds(Frame& F) {
;     ...
;         } else { const int it = item - 2048, bh = it >> 5, qb = it & 31, b = bh >> 3, h = bh & 7; float q2 = 0.f, sm = 3.0e38f;
; #pragma unroll
;             for (int r = 0; r < 4; ++r) { const int i = qb * 256 + F.lane + 64 * r; const size_t row = (size_t)b * SEQ + i;
;                 const v4u* qp = (const v4u*)(QO + row * DM + 512 + h * 64); const v4u* kp = (const v4u*)(FK + row * 512 + h * 64); float qq = 0.f, qk = 0.f;
; #pragma unroll
;                 for (int d8 = 0; d8 < 8; ++d8) { const v4u qv = qp[d8]; qq += sq8(qv); qk += dot8(qv, kp[d8]); }
;                 q2 = fmaxf(q2, qq); sm = fminf(sm, qk - C2[(size_t)bh * SEQ + i]); }
.LBB0_607:
	s_add_i32 s15, s29, 0x800
	s_cmpk_gt_i32 s15, 0x7ff
	s_mov_b64 s[6:7], -1
	s_cbranch_scc0 .LBB0_611
	s_lshr_b32 s68, s29, 8
	s_and_b32 s2, s31, 0x1f00
	v_or_b32_e32 v8, s2, v4
	s_lshl_b64 s[38:39], s[68:69], 13
	v_or_b32_e32 v0, s38, v8
	s_waitcnt lgkmcnt(0)
	v_mov_b32_e32 v1, s39
	s_lshl_b32 s2, s29, 2
	v_lshlrev_b64 v[2:3], 11, v[0:1]
	s_and_b32 s68, s2, 0x380
	v_lshl_add_u64 v[2:3], s[10:11], 0, v[2:3]
	v_lshl_add_u64 v[10:11], v[2:3], 0, s[68:69]
	s_mov_b64 s[38:39], 0x5a00400
	s_mov_b32 s2, 0x5a00000
	v_lshl_add_u64 v[6:7], v[10:11], 0, s[38:39]
	v_add_co_u32_e32 v10, vcc, s2, v10
	s_lshr_b32 s24, s29, 5
	s_nop 0
	v_addc_co_u32_e32 v11, vcc, 0, v11, vcc
	s_add_u32 s6, s16, s68
	s_addc_u32 s7, s17, 0
	v_lshlrev_b64 v[2:3], 10, v[0:1]
	v_lshl_add_u64 v[2:3], s[6:7], 0, v[2:3]
	s_mov_b32 s25, s69
	s_lshl_b64 s[24:25], s[24:25], 15
	s_add_u32 s24, s12, s24
	s_addc_u32 s25, s13, s25
	v_lshlrev_b32_e32 v192, 2, v8
	global_load_dwordx4 v[32:35], v[10:11], off offset:1024
	global_load_dwordx4 v[36:39], v[2:3], off
	global_load_dwordx4 v[40:43], v[6:7], off offset:16
	global_load_dwordx4 v[44:47], v[2:3], off offset:16
	global_load_dwordx4 v[48:51], v[6:7], off offset:32
	global_load_dwordx4 v[52:55], v[2:3], off offset:32
	global_load_dwordx4 v[56:59], v[6:7], off offset:48
	global_load_dwordx4 v[60:63], v[2:3], off offset:48
	global_load_dwordx4 v[64:67], v[6:7], off offset:64
	global_load_dwordx4 v[68:71], v[2:3], off offset:64
	global_load_dwordx4 v[72:75], v[6:7], off offset:80
	global_load_dwordx4 v[76:79], v[2:3], off offset:80
	global_load_dwordx4 v[80:83], v[6:7], off offset:96
	global_load_dwordx4 v[84:87], v[2:3], off offset:96
	global_load_dwordx4 v[88:91], v[6:7], off offset:112
	global_load_dwordx4 v[92:95], v[2:3], off offset:112
	s_waitcnt vmcnt(15)
	v_and_b32_e32 v14, 0xffff0000, v32
	v_and_b32_e32 v16, 0xffff0000, v33
	v_lshlrev_b32_e32 v9, 16, v32
	v_lshlrev_b32_e32 v15, 16, v33
	v_mul_f32_e32 v10, v14, v14
	v_mul_f32_e32 v11, v16, v16
	v_and_b32_e32 v18, 0xffff0000, v34
	v_fmac_f32_e32 v10, v9, v9
	v_fmac_f32_e32 v11, v15, v15
	v_lshlrev_b32_e32 v17, 16, v34
	v_add_f32_e32 v10, v10, v11
	v_mul_f32_e32 v11, v18, v18
	v_and_b32_e32 v20, 0xffff0000, v35
	v_fmac_f32_e32 v11, v17, v17
	v_lshlrev_b32_e32 v19, 16, v35
	v_add_f32_e32 v10, v11, v10
	v_mul_f32_e32 v11, v20, v20
	v_fmac_f32_e32 v11, v19, v19
	v_add_f32_e32 v21, v11, v10
	s_waitcnt vmcnt(14)
	v_lshlrev_b32_e32 v22, 16, v36
	v_and_b32_e32 v10, 0xffff0000, v36
	v_mul_f32_e32 v10, v14, v10
	v_fmac_f32_e32 v10, v9, v22
	v_lshlrev_b32_e32 v9, 16, v37
	v_and_b32_e32 v11, 0xffff0000, v37
	v_mul_f32_e32 v11, v16, v11
	v_fmac_f32_e32 v11, v15, v9
	v_add_f32_e32 v9, v10, v11
	v_and_b32_e32 v11, 0xffff0000, v38
	v_lshlrev_b32_e32 v10, 16, v38
	v_mul_f32_e32 v11, v18, v11
	v_fmac_f32_e32 v11, v17, v10
	v_add_f32_e32 v9, v11, v9
	v_and_b32_e32 v11, 0xffff0000, v39
	v_lshlrev_b32_e32 v10, 16, v39
	v_mul_f32_e32 v11, v20, v11
	v_fmac_f32_e32 v11, v19, v10
	v_add_f32_e32 v9, v11, v9
	v_add_f32_e32 v9, 0, v9
	s_waitcnt vmcnt(13)
	v_and_b32_e32 v15, 0xffff0000, v40
	v_and_b32_e32 v17, 0xffff0000, v41
	v_lshlrev_b32_e32 v14, 16, v40
	v_lshlrev_b32_e32 v16, 16, v41
	v_mul_f32_e32 v10, v15, v15
	v_mul_f32_e32 v11, v17, v17
	v_and_b32_e32 v19, 0xffff0000, v42
	v_fmac_f32_e32 v10, v14, v14
	v_fmac_f32_e32 v11, v16, v16
	v_lshlrev_b32_e32 v18, 16, v42
	v_add_f32_e32 v10, v10, v11
	v_mul_f32_e32 v11, v19, v19
	v_and_b32_e32 v22, 0xffff0000, v43
	v_fmac_f32_e32 v11, v18, v18
	v_lshlrev_b32_e32 v20, 16, v43
	v_add_f32_e32 v10, v11, v10
	v_mul_f32_e32 v11, v22, v22
	v_fmac_f32_e32 v11, v20, v20
	v_add_f32_e32 v10, v11, v10
	v_add_f32_e32 v21, v21, v10
	s_waitcnt vmcnt(12)
	v_lshlrev_b32_e32 v23, 16, v44
	v_and_b32_e32 v10, 0xffff0000, v44
	v_mul_f32_e32 v10, v15, v10
	v_fmac_f32_e32 v10, v14, v23
	v_lshlrev_b32_e32 v14, 16, v45
	v_and_b32_e32 v11, 0xffff0000, v45
	v_mul_f32_e32 v11, v17, v11
	v_fmac_f32_e32 v11, v16, v14
	v_add_f32_e32 v10, v10, v11
	v_lshlrev_b32_e32 v11, 16, v46
	v_and_b32_e32 v12, 0xffff0000, v46
	v_mul_f32_e32 v12, v19, v12
	v_fmac_f32_e32 v12, v18, v11
	v_add_f32_e32 v10, v12, v10
	v_and_b32_e32 v12, 0xffff0000, v47
	v_lshlrev_b32_e32 v11, 16, v47
	v_mul_f32_e32 v12, v22, v12
	v_fmac_f32_e32 v12, v20, v11
	v_add_f32_e32 v10, v12, v10
	v_add_f32_e32 v9, v9, v10
	s_waitcnt vmcnt(11)
	v_and_b32_e32 v15, 0xffff0000, v48
	v_and_b32_e32 v17, 0xffff0000, v49
	v_lshlrev_b32_e32 v14, 16, v48
	v_lshlrev_b32_e32 v16, 16, v49
	v_mul_f32_e32 v10, v15, v15
	v_mul_f32_e32 v11, v17, v17
	v_and_b32_e32 v19, 0xffff0000, v50
	v_fmac_f32_e32 v10, v14, v14
	v_fmac_f32_e32 v11, v16, v16
	v_lshlrev_b32_e32 v18, 16, v50
	v_add_f32_e32 v10, v10, v11
	v_mul_f32_e32 v11, v19, v19
	v_and_b32_e32 v22, 0xffff0000, v51
	v_fmac_f32_e32 v11, v18, v18
	v_lshlrev_b32_e32 v20, 16, v51
	v_add_f32_e32 v10, v11, v10
	v_mul_f32_e32 v11, v22, v22
	v_fmac_f32_e32 v11, v20, v20
	v_add_f32_e32 v10, v11, v10
	v_add_f32_e32 v21, v21, v10
	s_waitcnt vmcnt(10)
	v_lshlrev_b32_e32 v23, 16, v52
	v_and_b32_e32 v10, 0xffff0000, v52
	v_mul_f32_e32 v10, v15, v10
	v_fmac_f32_e32 v10, v14, v23
	v_lshlrev_b32_e32 v14, 16, v53
	v_and_b32_e32 v11, 0xffff0000, v53
	v_mul_f32_e32 v11, v17, v11
	v_fmac_f32_e32 v11, v16, v14
	v_add_f32_e32 v10, v10, v11
	v_lshlrev_b32_e32 v11, 16, v54
	v_and_b32_e32 v12, 0xffff0000, v54
	v_mul_f32_e32 v12, v19, v12
	v_fmac_f32_e32 v12, v18, v11
	v_add_f32_e32 v10, v12, v10
	v_and_b32_e32 v12, 0xffff0000, v55
	v_lshlrev_b32_e32 v11, 16, v55
	v_mul_f32_e32 v12, v22, v12
	v_fmac_f32_e32 v12, v20, v11
	v_add_f32_e32 v10, v12, v10
	v_add_f32_e32 v9, v9, v10
	s_waitcnt vmcnt(9)
; __device__ __forceinline__ float bflo(unsigned w) { return __uint_as_float(w << 16); }
; __device__ __forceinline__ float bfhi(unsigned w) { return __uint_as_float(w & 0xffff0000u); }
; __device__ __forceinline__ float sq8(const v4u w) { const float a0 = bflo(w.x), a1 = bfhi(w.x), a2 = bflo(w.y), a3 = bfhi(w.y), a4 = bflo(w.z), a5 = bfhi(w.z), a6 = bflo(w.w), a7 = bfhi(w.w); return (a0 * a0 + a1 * a1) + (a2 * a2 + a3 * a3) + (a4 * a4 + a5 * a5) + (a6 * a6 + a7 * a7); }
; __device__ __forceinline__ float dot8(const v4u a, const v4u b) { return (bflo(a.x) * bflo(b.x) + bfhi(a.x) * bfhi(b.x)) + (bflo(a.y) * bflo(b.y) + bfhi(a.y) * bfhi(b.y)) + (bflo(a.z) * bflo(b.z) + bfhi(a.z) * bfhi(b.z)) + (bflo(a.w) * bflo(b.w) + bfhi(a.w) * bfhi(b.w)); }
; __device__ __forceinline__ void fox_bounds(Frame& F) {
;     ...
;             for (int r = 0; r < 4; ++r) { const int i = qb * 256 + F.lane + 64 * r; const size_t row = (size_t)b * SEQ + i;
;                 const v4u* qp = (const v4u*)(QO + row * DM + 512 + h * 64); const v4u* kp = (const v4u*)(FK + row * 512 + h * 64); float qq = 0.f, qk = 0.f;
; #pragma unroll
;                 for (int d8 = 0; d8 < 8; ++d8) { const v4u qv = qp[d8]; qq += sq8(qv); qk += dot8(qv, kp[d8]); }
	v_and_b32_e32 v15, 0xffff0000, v56
	v_and_b32_e32 v17, 0xffff0000, v57
	v_lshlrev_b32_e32 v14, 16, v56
	v_lshlrev_b32_e32 v16, 16, v57
	v_mul_f32_e32 v10, v15, v15
	v_mul_f32_e32 v11, v17, v17
	v_and_b32_e32 v19, 0xffff0000, v58
	v_fmac_f32_e32 v10, v14, v14
	v_fmac_f32_e32 v11, v16, v16
	v_lshlrev_b32_e32 v18, 16, v58
	v_add_f32_e32 v10, v10, v11
	v_mul_f32_e32 v11, v19, v19
	v_and_b32_e32 v22, 0xffff0000, v59
	v_fmac_f32_e32 v11, v18, v18
	v_lshlrev_b32_e32 v20, 16, v59
	v_add_f32_e32 v10, v11, v10
	v_mul_f32_e32 v11, v22, v22
	v_fmac_f32_e32 v11, v20, v20
	v_add_f32_e32 v10, v11, v10
	v_add_f32_e32 v21, v21, v10
	s_waitcnt vmcnt(8)
	v_lshlrev_b32_e32 v23, 16, v60
	v_and_b32_e32 v10, 0xffff0000, v60
	v_mul_f32_e32 v10, v15, v10
	v_fmac_f32_e32 v10, v14, v23
	v_lshlrev_b32_e32 v14, 16, v61
	v_and_b32_e32 v11, 0xffff0000, v61
	v_mul_f32_e32 v11, v17, v11
	v_fmac_f32_e32 v11, v16, v14
	v_add_f32_e32 v10, v10, v11
	v_lshlrev_b32_e32 v11, 16, v62
	v_and_b32_e32 v12, 0xffff0000, v62
	v_mul_f32_e32 v12, v19, v12
	v_fmac_f32_e32 v12, v18, v11
	v_add_f32_e32 v10, v12, v10
	v_and_b32_e32 v12, 0xffff0000, v63
	v_lshlrev_b32_e32 v11, 16, v63
	v_mul_f32_e32 v12, v22, v12
	v_fmac_f32_e32 v12, v20, v11
	v_add_f32_e32 v10, v12, v10
	v_add_f32_e32 v9, v9, v10
	s_waitcnt vmcnt(7)
	v_and_b32_e32 v15, 0xffff0000, v64
	v_and_b32_e32 v17, 0xffff0000, v65
	v_lshlrev_b32_e32 v14, 16, v64
	v_lshlrev_b32_e32 v16, 16, v65
	v_mul_f32_e32 v10, v15, v15
	v_mul_f32_e32 v11, v17, v17
	v_and_b32_e32 v19, 0xffff0000, v66
	v_fmac_f32_e32 v10, v14, v14
	v_fmac_f32_e32 v11, v16, v16
	v_lshlrev_b32_e32 v18, 16, v66
	v_add_f32_e32 v10, v10, v11
	v_mul_f32_e32 v11, v19, v19
	v_and_b32_e32 v22, 0xffff0000, v67
	v_fmac_f32_e32 v11, v18, v18
	v_lshlrev_b32_e32 v20, 16, v67
	v_add_f32_e32 v10, v11, v10
	v_mul_f32_e32 v11, v22, v22
	v_fmac_f32_e32 v11, v20, v20
	v_add_f32_e32 v10, v11, v10
	v_add_f32_e32 v21, v21, v10
	s_waitcnt vmcnt(6)
	v_lshlrev_b32_e32 v23, 16, v68
	v_and_b32_e32 v10, 0xffff0000, v68
	v_mul_f32_e32 v10, v15, v10
	v_fmac_f32_e32 v10, v14, v23
	v_lshlrev_b32_e32 v14, 16, v69
	v_and_b32_e32 v11, 0xffff0000, v69
	v_mul_f32_e32 v11, v17, v11
	v_fmac_f32_e32 v11, v16, v14
	v_add_f32_e32 v10, v10, v11
	v_lshlrev_b32_e32 v11, 16, v70
	v_and_b32_e32 v12, 0xffff0000, v70
	v_mul_f32_e32 v12, v19, v12
	v_fmac_f32_e32 v12, v18, v11
	v_add_f32_e32 v10, v12, v10
	v_and_b32_e32 v12, 0xffff0000, v71
	v_lshlrev_b32_e32 v11, 16, v71
	v_mul_f32_e32 v12, v22, v12
	v_fmac_f32_e32 v12, v20, v11
	v_add_f32_e32 v10, v12, v10
	v_add_f32_e32 v9, v9, v10
	s_waitcnt vmcnt(5)
	v_and_b32_e32 v15, 0xffff0000, v72
	v_and_b32_e32 v17, 0xffff0000, v73
	v_lshlrev_b32_e32 v14, 16, v72
	v_lshlrev_b32_e32 v16, 16, v73
	v_mul_f32_e32 v10, v15, v15
	v_mul_f32_e32 v11, v17, v17
	v_and_b32_e32 v19, 0xffff0000, v74
	v_fmac_f32_e32 v10, v14, v14
	v_fmac_f32_e32 v11, v16, v16
	v_lshlrev_b32_e32 v18, 16, v74
	v_add_f32_e32 v10, v10, v11
	v_mul_f32_e32 v11, v19, v19
	v_and_b32_e32 v22, 0xffff0000, v75
	v_fmac_f32_e32 v11, v18, v18
	v_lshlrev_b32_e32 v20, 16, v75
	v_add_f32_e32 v10, v11, v10
	v_mul_f32_e32 v11, v22, v22
	v_fmac_f32_e32 v11, v20, v20
	v_add_f32_e32 v10, v11, v10
	v_add_f32_e32 v21, v21, v10
	s_waitcnt vmcnt(4)
	v_lshlrev_b32_e32 v23, 16, v76
	v_and_b32_e32 v10, 0xffff0000, v76
	v_mul_f32_e32 v10, v15, v10
	v_fmac_f32_e32 v10, v14, v23
	v_lshlrev_b32_e32 v14, 16, v77
	v_and_b32_e32 v11, 0xffff0000, v77
	v_mul_f32_e32 v11, v17, v11
	v_fmac_f32_e32 v11, v16, v14
	v_add_f32_e32 v10, v10, v11
	v_lshlrev_b32_e32 v11, 16, v78
	v_and_b32_e32 v12, 0xffff0000, v78
	v_mul_f32_e32 v12, v19, v12
	v_fmac_f32_e32 v12, v18, v11
	v_add_f32_e32 v10, v12, v10
	v_and_b32_e32 v12, 0xffff0000, v79
	v_lshlrev_b32_e32 v11, 16, v79
	v_mul_f32_e32 v12, v22, v12
	v_fmac_f32_e32 v12, v20, v11
	v_add_f32_e32 v10, v12, v10
	v_add_f32_e32 v9, v9, v10
	s_waitcnt vmcnt(3)
	v_and_b32_e32 v17, 0xffff0000, v80
	v_lshlrev_b32_e32 v18, 16, v81
	v_and_b32_e32 v11, 0xffff0000, v81
	v_lshlrev_b32_e32 v16, 16, v80
	v_lshlrev_b32_e32 v19, 16, v82
	v_and_b32_e32 v20, 0xffff0000, v82
	v_mul_f32_e32 v10, v17, v17
	v_mul_f32_e32 v12, v11, v11
	v_fmac_f32_e32 v10, v16, v16
	v_fmac_f32_e32 v12, v18, v18
	v_add_f32_e32 v10, v10, v12
	v_mul_f32_e32 v12, v20, v20
	v_and_b32_e32 v23, 0xffff0000, v83
	v_fmac_f32_e32 v12, v19, v19
	v_lshlrev_b32_e32 v22, 16, v83
	v_add_f32_e32 v10, v12, v10
	v_mul_f32_e32 v12, v23, v23
	v_fmac_f32_e32 v12, v22, v22
	v_add_f32_e32 v10, v12, v10
	v_add_f32_e32 v10, v21, v10
	s_waitcnt vmcnt(2)
	v_lshlrev_b32_e32 v21, 16, v84
	v_and_b32_e32 v12, 0xffff0000, v84
	v_mul_f32_e32 v12, v17, v12
	v_fmac_f32_e32 v12, v16, v21
	v_lshlrev_b32_e32 v16, 16, v85
	v_and_b32_e32 v13, 0xffff0000, v85
	v_mul_f32_e32 v11, v11, v13
	v_fmac_f32_e32 v11, v18, v16
	v_and_b32_e32 v13, 0xffff0000, v86
	v_add_f32_e32 v11, v12, v11
	v_lshlrev_b32_e32 v12, 16, v86
	v_mul_f32_e32 v13, v20, v13
	v_fmac_f32_e32 v13, v19, v12
	v_add_f32_e32 v11, v13, v11
	v_and_b32_e32 v13, 0xffff0000, v87
	v_lshlrev_b32_e32 v12, 16, v87
	v_mul_f32_e32 v13, v23, v13
	v_fmac_f32_e32 v13, v22, v12
	v_add_f32_e32 v11, v13, v11
	v_add_f32_e32 v9, v9, v11
	s_waitcnt vmcnt(1)
	v_and_b32_e32 v7, 0xffff0000, v88
	v_and_b32_e32 v17, 0xffff0000, v89
	v_lshlrev_b32_e32 v6, 16, v88
	v_lshlrev_b32_e32 v16, 16, v89
	v_mul_f32_e32 v11, v7, v7
	v_mul_f32_e32 v12, v17, v17
	v_and_b32_e32 v19, 0xffff0000, v90
	v_fmac_f32_e32 v11, v6, v6
	v_fmac_f32_e32 v12, v16, v16
	v_lshlrev_b32_e32 v18, 16, v90
	v_add_f32_e32 v11, v11, v12
	v_mul_f32_e32 v12, v19, v19
	v_and_b32_e32 v21, 0xffff0000, v91
	v_fmac_f32_e32 v12, v18, v18
	v_lshlrev_b32_e32 v20, 16, v91
	v_add_f32_e32 v11, v12, v11
	v_mul_f32_e32 v12, v21, v21
	v_fmac_f32_e32 v12, v20, v20
	v_add_f32_e32 v11, v12, v11
	v_add_f32_e32 v11, v10, v11
	s_waitcnt vmcnt(0)
; __device__ __forceinline__ float bflo(unsigned w) { return __uint_as_float(w << 16); }
; __device__ __forceinline__ float bfhi(unsigned w) { return __uint_as_float(w & 0xffff0000u); }
; __device__ __forceinline__ float sq8(const v4u w) { const float a0 = bflo(w.x), a1 = bfhi(w.x), a2 = bflo(w.y), a3 = bfhi(w.y), a4 = bflo(w.z), a5 = bfhi(w.z), a6 = bflo(w.w), a7 = bfhi(w.w); return (a0 * a0 + a1 * a1) + (a2 * a2 + a3 * a3) + (a4 * a4 + a5 * a5) + (a6 * a6 + a7 * a7); }
; __device__ __forceinline__ float dot8(const v4u a, const v4u b) { return (bflo(a.x) * bflo(b.x) + bfhi(a.x) * bfhi(b.x)) + (bflo(a.y) * bflo(b.y) + bfhi(a.y) * bfhi(b.y)) + (bflo(a.z) * bflo(b.z) + bfhi(a.z) * bfhi(b.z)) + (bflo(a.w) * bflo(b.w) + bfhi(a.w) * bfhi(b.w)); }
; __device__ __forceinline__ void fox_bounds(Frame& F) {
;     ...
;             for (int r = 0; r < 4; ++r) { const int i = qb * 256 + F.lane + 64 * r; const size_t row = (size_t)b * SEQ + i;
;                 const v4u* qp = (const v4u*)(QO + row * DM + 512 + h * 64); const v4u* kp = (const v4u*)(FK + row * 512 + h * 64); float qq = 0.f, qk = 0.f;
; #pragma unroll
;                 for (int d8 = 0; d8 < 8; ++d8) { const v4u qv = qp[d8]; qq += sq8(qv); qk += dot8(qv, kp[d8]); }
;                 q2 = fmaxf(q2, qq); sm = fminf(sm, qk - C2[(size_t)bh * SEQ + i]); }
	v_mov_b32_e32 v12, v92
	v_mov_b32_e32 v13, v93
	v_mov_b32_e32 v14, v94
	v_mov_b32_e32 v15, v95
	v_and_b32_e32 v3, 0xffff0000, v12
	v_lshlrev_b32_e32 v2, 16, v12
	v_mul_f32_e32 v3, v7, v3
	v_fmac_f32_e32 v3, v6, v2
	v_and_b32_e32 v6, 0xffff0000, v13
	v_lshlrev_b32_e32 v2, 16, v13
	v_mul_f32_e32 v6, v17, v6
	v_fmac_f32_e32 v6, v16, v2
	v_add_f32_e32 v2, v3, v6
	v_and_b32_e32 v6, 0xffff0000, v14
	v_lshlrev_b32_e32 v3, 16, v14
	v_mul_f32_e32 v6, v19, v6
	v_fmac_f32_e32 v6, v18, v3
	v_add_f32_e32 v2, v6, v2
	v_and_b32_e32 v6, 0xffff0000, v15
	v_lshlrev_b32_e32 v3, 16, v15
	v_mul_f32_e32 v6, v21, v6
	v_fmac_f32_e32 v6, v20, v3
	v_add_f32_e32 v2, v6, v2
	v_add_f32_e32 v6, v9, v2
	v_lshl_add_u64 v[2:3], s[24:25], 0, v[192:193]
	flat_load_dword v7, v[2:3]
	s_waitcnt vmcnt(0) lgkmcnt(0)
	v_sub_f32_e32 v10, v6, v7
	v_or_b32_e32 v6, 64, v0
	v_mov_b32_e32 v7, v1
	v_lshlrev_b64 v[8:9], 11, v[6:7]
	v_lshl_add_u64 v[8:9], s[10:11], 0, v[8:9]
	v_lshl_add_u64 v[12:13], v[8:9], 0, s[68:69]
	v_lshl_add_u64 v[8:9], v[12:13], 0, s[38:39]
	v_add_co_u32_e32 v12, vcc, s2, v12
	v_lshlrev_b64 v[6:7], 10, v[6:7]
	s_nop 0
	v_addc_co_u32_e32 v13, vcc, 0, v13, vcc
	v_lshl_add_u64 v[6:7], s[6:7], 0, v[6:7]
	global_load_dwordx4 v[32:35], v[12:13], off offset:1024
	global_load_dwordx4 v[36:39], v[6:7], off
	global_load_dwordx4 v[40:43], v[8:9], off offset:16
	global_load_dwordx4 v[44:47], v[6:7], off offset:16
	global_load_dwordx4 v[48:51], v[8:9], off offset:32
	global_load_dwordx4 v[52:55], v[6:7], off offset:32
	global_load_dwordx4 v[56:59], v[8:9], off offset:48
	global_load_dwordx4 v[60:63], v[6:7], off offset:48
	global_load_dwordx4 v[64:67], v[8:9], off offset:64
	global_load_dwordx4 v[68:71], v[6:7], off offset:64
	global_load_dwordx4 v[72:75], v[8:9], off offset:80
	global_load_dwordx4 v[76:79], v[6:7], off offset:80
	global_load_dwordx4 v[80:83], v[8:9], off offset:96
	global_load_dwordx4 v[84:87], v[6:7], off offset:96
	global_load_dwordx4 v[88:91], v[8:9], off offset:112
	global_load_dwordx4 v[92:95], v[6:7], off offset:112
	global_load_dword v96, v[2:3], off offset:256
	s_waitcnt vmcnt(16)
	v_and_b32_e32 v17, 0xffff0000, v32
	v_and_b32_e32 v19, 0xffff0000, v33
	v_lshlrev_b32_e32 v16, 16, v32
	v_lshlrev_b32_e32 v18, 16, v33
	v_mul_f32_e32 v12, v17, v17
	v_mul_f32_e32 v13, v19, v19
	v_and_b32_e32 v21, 0xffff0000, v34
	v_fmac_f32_e32 v12, v16, v16
	v_fmac_f32_e32 v13, v18, v18
	v_lshlrev_b32_e32 v20, 16, v34
	v_add_f32_e32 v12, v12, v13
	v_mul_f32_e32 v13, v21, v21
	v_and_b32_e32 v23, 0xffff0000, v35
	v_fmac_f32_e32 v13, v20, v20
	v_lshlrev_b32_e32 v22, 16, v35
	v_add_f32_e32 v12, v13, v12
	v_mul_f32_e32 v13, v23, v23
	v_fmac_f32_e32 v13, v22, v22
	v_add_f32_e32 v24, v13, v12
	s_waitcnt vmcnt(15)
	v_lshlrev_b32_e32 v25, 16, v36
	v_and_b32_e32 v12, 0xffff0000, v36
	v_mul_f32_e32 v12, v17, v12
	v_fmac_f32_e32 v12, v16, v25
	v_lshlrev_b32_e32 v16, 16, v37
	v_and_b32_e32 v13, 0xffff0000, v37
	v_mul_f32_e32 v13, v19, v13
	v_fmac_f32_e32 v13, v18, v16
	v_add_f32_e32 v12, v12, v13
	v_lshlrev_b32_e32 v13, 16, v38
	v_and_b32_e32 v14, 0xffff0000, v38
	v_mul_f32_e32 v14, v21, v14
	v_fmac_f32_e32 v14, v20, v13
	v_add_f32_e32 v12, v14, v12
	v_and_b32_e32 v14, 0xffff0000, v39
	v_lshlrev_b32_e32 v13, 16, v39
	v_mul_f32_e32 v14, v23, v14
	v_fmac_f32_e32 v14, v22, v13
	v_add_f32_e32 v12, v14, v12
	v_add_f32_e32 v16, 0, v12
	s_waitcnt vmcnt(14)
	v_and_b32_e32 v18, 0xffff0000, v40
	v_and_b32_e32 v20, 0xffff0000, v41
	v_lshlrev_b32_e32 v17, 16, v40
	v_lshlrev_b32_e32 v19, 16, v41
	v_mul_f32_e32 v12, v18, v18
	v_mul_f32_e32 v13, v20, v20
	v_and_b32_e32 v22, 0xffff0000, v42
	v_fmac_f32_e32 v12, v17, v17
	v_fmac_f32_e32 v13, v19, v19
	v_lshlrev_b32_e32 v21, 16, v42
	v_add_f32_e32 v12, v12, v13
	v_mul_f32_e32 v13, v22, v22
	v_and_b32_e32 v25, 0xffff0000, v43
	v_fmac_f32_e32 v13, v21, v21
	v_lshlrev_b32_e32 v23, 16, v43
	v_add_f32_e32 v12, v13, v12
	v_mul_f32_e32 v13, v25, v25
	v_fmac_f32_e32 v13, v23, v23
	v_add_f32_e32 v12, v13, v12
	v_add_f32_e32 v24, v24, v12
	s_waitcnt vmcnt(13)
	v_lshlrev_b32_e32 v26, 16, v44
	v_and_b32_e32 v12, 0xffff0000, v44
	v_mul_f32_e32 v12, v18, v12
	v_fmac_f32_e32 v12, v17, v26
	v_lshlrev_b32_e32 v17, 16, v45
	v_and_b32_e32 v13, 0xffff0000, v45
	v_mul_f32_e32 v13, v20, v13
	v_fmac_f32_e32 v13, v19, v17
	v_add_f32_e32 v12, v12, v13
	v_lshlrev_b32_e32 v13, 16, v46
	v_and_b32_e32 v14, 0xffff0000, v46
	v_mul_f32_e32 v14, v22, v14
	v_fmac_f32_e32 v14, v21, v13
	v_add_f32_e32 v12, v14, v12
	v_and_b32_e32 v14, 0xffff0000, v47
	v_lshlrev_b32_e32 v13, 16, v47
	v_mul_f32_e32 v14, v25, v14
	v_fmac_f32_e32 v14, v23, v13
	v_add_f32_e32 v12, v14, v12
	v_add_f32_e32 v16, v16, v12
	s_waitcnt vmcnt(12)
	v_and_b32_e32 v18, 0xffff0000, v48
	v_and_b32_e32 v20, 0xffff0000, v49
	v_lshlrev_b32_e32 v17, 16, v48
	v_lshlrev_b32_e32 v19, 16, v49
	v_mul_f32_e32 v12, v18, v18
	v_mul_f32_e32 v13, v20, v20
	v_and_b32_e32 v22, 0xffff0000, v50
	v_fmac_f32_e32 v12, v17, v17
	v_fmac_f32_e32 v13, v19, v19
	v_lshlrev_b32_e32 v21, 16, v50
	v_add_f32_e32 v12, v12, v13
	v_mul_f32_e32 v13, v22, v22
	v_and_b32_e32 v25, 0xffff0000, v51
	v_fmac_f32_e32 v13, v21, v21
	v_lshlrev_b32_e32 v23, 16, v51
	v_add_f32_e32 v12, v13, v12
	v_mul_f32_e32 v13, v25, v25
	v_fmac_f32_e32 v13, v23, v23
	v_add_f32_e32 v12, v13, v12
	v_add_f32_e32 v24, v24, v12
	s_waitcnt vmcnt(11)
	v_lshlrev_b32_e32 v26, 16, v52
	v_and_b32_e32 v12, 0xffff0000, v52
	v_mul_f32_e32 v12, v18, v12
	v_fmac_f32_e32 v12, v17, v26
	v_lshlrev_b32_e32 v17, 16, v53
	v_and_b32_e32 v13, 0xffff0000, v53
	v_mul_f32_e32 v13, v20, v13
	v_fmac_f32_e32 v13, v19, v17
	v_add_f32_e32 v12, v12, v13
	v_lshlrev_b32_e32 v13, 16, v54
	v_and_b32_e32 v14, 0xffff0000, v54
	v_mul_f32_e32 v14, v22, v14
	v_fmac_f32_e32 v14, v21, v13
	v_add_f32_e32 v12, v14, v12
	v_and_b32_e32 v14, 0xffff0000, v55
	v_lshlrev_b32_e32 v13, 16, v55
	v_mul_f32_e32 v14, v25, v14
	v_fmac_f32_e32 v14, v23, v13
	v_add_f32_e32 v12, v14, v12
	v_add_f32_e32 v16, v16, v12
	s_waitcnt vmcnt(10)
; __device__ __forceinline__ float bflo(unsigned w) { return __uint_as_float(w << 16); }
; __device__ __forceinline__ float bfhi(unsigned w) { return __uint_as_float(w & 0xffff0000u); }
; __device__ __forceinline__ float sq8(const v4u w) { const float a0 = bflo(w.x), a1 = bfhi(w.x), a2 = bflo(w.y), a3 = bfhi(w.y), a4 = bflo(w.z), a5 = bfhi(w.z), a6 = bflo(w.w), a7 = bfhi(w.w); return (a0 * a0 + a1 * a1) + (a2 * a2 + a3 * a3) + (a4 * a4 + a5 * a5) + (a6 * a6 + a7 * a7); }
; __device__ __forceinline__ float dot8(const v4u a, const v4u b) { return (bflo(a.x) * bflo(b.x) + bfhi(a.x) * bfhi(b.x)) + (bflo(a.y) * bflo(b.y) + bfhi(a.y) * bfhi(b.y)) + (bflo(a.z) * bflo(b.z) + bfhi(a.z) * bfhi(b.z)) + (bflo(a.w) * bflo(b.w) + bfhi(a.w) * bfhi(b.w)); }
; __device__ __forceinline__ void fox_bounds(Frame& F) {
;     ...
;             for (int r = 0; r < 4; ++r) { const int i = qb * 256 + F.lane + 64 * r; const size_t row = (size_t)b * SEQ + i;
;                 const v4u* qp = (const v4u*)(QO + row * DM + 512 + h * 64); const v4u* kp = (const v4u*)(FK + row * 512 + h * 64); float qq = 0.f, qk = 0.f;
; #pragma unroll
;                 for (int d8 = 0; d8 < 8; ++d8) { const v4u qv = qp[d8]; qq += sq8(qv); qk += dot8(qv, kp[d8]); }
	v_and_b32_e32 v18, 0xffff0000, v56
	v_and_b32_e32 v20, 0xffff0000, v57
	v_lshlrev_b32_e32 v17, 16, v56
	v_lshlrev_b32_e32 v19, 16, v57
	v_mul_f32_e32 v12, v18, v18
	v_mul_f32_e32 v13, v20, v20
	v_and_b32_e32 v22, 0xffff0000, v58
	v_fmac_f32_e32 v12, v17, v17
	v_fmac_f32_e32 v13, v19, v19
	v_lshlrev_b32_e32 v21, 16, v58
	v_add_f32_e32 v12, v12, v13
	v_mul_f32_e32 v13, v22, v22
	v_and_b32_e32 v25, 0xffff0000, v59
	v_fmac_f32_e32 v13, v21, v21
	v_lshlrev_b32_e32 v23, 16, v59
	v_add_f32_e32 v12, v13, v12
	v_mul_f32_e32 v13, v25, v25
	v_fmac_f32_e32 v13, v23, v23
	v_add_f32_e32 v12, v13, v12
	v_add_f32_e32 v24, v24, v12
	s_waitcnt vmcnt(9)
	v_lshlrev_b32_e32 v26, 16, v60
	v_and_b32_e32 v12, 0xffff0000, v60
	v_mul_f32_e32 v12, v18, v12
	v_fmac_f32_e32 v12, v17, v26
	v_lshlrev_b32_e32 v17, 16, v61
	v_and_b32_e32 v13, 0xffff0000, v61
	v_mul_f32_e32 v13, v20, v13
	v_fmac_f32_e32 v13, v19, v17
	v_add_f32_e32 v12, v12, v13
	v_lshlrev_b32_e32 v13, 16, v62
	v_and_b32_e32 v14, 0xffff0000, v62
	v_mul_f32_e32 v14, v22, v14
	v_fmac_f32_e32 v14, v21, v13
	v_add_f32_e32 v12, v14, v12
	v_and_b32_e32 v14, 0xffff0000, v63
	v_lshlrev_b32_e32 v13, 16, v63
	v_mul_f32_e32 v14, v25, v14
	v_fmac_f32_e32 v14, v23, v13
	v_add_f32_e32 v12, v14, v12
	v_add_f32_e32 v16, v16, v12
	s_waitcnt vmcnt(8)
	v_and_b32_e32 v18, 0xffff0000, v64
	v_and_b32_e32 v20, 0xffff0000, v65
	v_lshlrev_b32_e32 v17, 16, v64
	v_lshlrev_b32_e32 v19, 16, v65
	v_mul_f32_e32 v12, v18, v18
	v_mul_f32_e32 v13, v20, v20
	v_and_b32_e32 v22, 0xffff0000, v66
	v_fmac_f32_e32 v12, v17, v17
	v_fmac_f32_e32 v13, v19, v19
	v_lshlrev_b32_e32 v21, 16, v66
	v_add_f32_e32 v12, v12, v13
	v_mul_f32_e32 v13, v22, v22
	v_and_b32_e32 v25, 0xffff0000, v67
	v_fmac_f32_e32 v13, v21, v21
	v_lshlrev_b32_e32 v23, 16, v67
	v_add_f32_e32 v12, v13, v12
	v_mul_f32_e32 v13, v25, v25
	v_fmac_f32_e32 v13, v23, v23
	v_add_f32_e32 v12, v13, v12
	v_add_f32_e32 v24, v24, v12
	s_waitcnt vmcnt(7)
	v_lshlrev_b32_e32 v26, 16, v68
	v_and_b32_e32 v12, 0xffff0000, v68
	v_mul_f32_e32 v12, v18, v12
	v_fmac_f32_e32 v12, v17, v26
	v_lshlrev_b32_e32 v17, 16, v69
	v_and_b32_e32 v13, 0xffff0000, v69
	v_mul_f32_e32 v13, v20, v13
	v_fmac_f32_e32 v13, v19, v17
	v_add_f32_e32 v12, v12, v13
	v_lshlrev_b32_e32 v13, 16, v70
	v_and_b32_e32 v14, 0xffff0000, v70
	v_mul_f32_e32 v14, v22, v14
	v_fmac_f32_e32 v14, v21, v13
	v_add_f32_e32 v12, v14, v12
	v_and_b32_e32 v14, 0xffff0000, v71
	v_lshlrev_b32_e32 v13, 16, v71
	v_mul_f32_e32 v14, v25, v14
	v_fmac_f32_e32 v14, v23, v13
	v_add_f32_e32 v12, v14, v12
	v_add_f32_e32 v16, v16, v12
	s_waitcnt vmcnt(6)
	v_and_b32_e32 v18, 0xffff0000, v72
	v_and_b32_e32 v20, 0xffff0000, v73
	v_lshlrev_b32_e32 v17, 16, v72
	v_lshlrev_b32_e32 v19, 16, v73
	v_mul_f32_e32 v12, v18, v18
	v_mul_f32_e32 v13, v20, v20
	v_and_b32_e32 v22, 0xffff0000, v74
	v_fmac_f32_e32 v12, v17, v17
	v_fmac_f32_e32 v13, v19, v19
	v_lshlrev_b32_e32 v21, 16, v74
	v_add_f32_e32 v12, v12, v13
	v_mul_f32_e32 v13, v22, v22
	v_and_b32_e32 v25, 0xffff0000, v75
	v_fmac_f32_e32 v13, v21, v21
	v_lshlrev_b32_e32 v23, 16, v75
	v_add_f32_e32 v12, v13, v12
	v_mul_f32_e32 v13, v25, v25
	v_fmac_f32_e32 v13, v23, v23
	v_add_f32_e32 v12, v13, v12
	v_add_f32_e32 v24, v24, v12
	s_waitcnt vmcnt(5)
	v_lshlrev_b32_e32 v26, 16, v76
	v_and_b32_e32 v12, 0xffff0000, v76
	v_mul_f32_e32 v12, v18, v12
	v_fmac_f32_e32 v12, v17, v26
	v_lshlrev_b32_e32 v17, 16, v77
	v_and_b32_e32 v13, 0xffff0000, v77
	v_mul_f32_e32 v13, v20, v13
	v_fmac_f32_e32 v13, v19, v17
	v_add_f32_e32 v12, v12, v13
	v_lshlrev_b32_e32 v13, 16, v78
	v_and_b32_e32 v14, 0xffff0000, v78
	v_mul_f32_e32 v14, v22, v14
	v_fmac_f32_e32 v14, v21, v13
	v_add_f32_e32 v12, v14, v12
	v_and_b32_e32 v14, 0xffff0000, v79
	v_lshlrev_b32_e32 v13, 16, v79
	v_mul_f32_e32 v14, v25, v14
	v_fmac_f32_e32 v14, v23, v13
	v_add_f32_e32 v12, v14, v12
	v_add_f32_e32 v16, v16, v12
	s_waitcnt vmcnt(4)
	v_and_b32_e32 v18, 0xffff0000, v80
	v_and_b32_e32 v20, 0xffff0000, v81
	v_lshlrev_b32_e32 v17, 16, v80
	v_lshlrev_b32_e32 v19, 16, v81
	v_mul_f32_e32 v12, v18, v18
	v_mul_f32_e32 v13, v20, v20
	v_and_b32_e32 v22, 0xffff0000, v82
	v_fmac_f32_e32 v12, v17, v17
	v_fmac_f32_e32 v13, v19, v19
	v_lshlrev_b32_e32 v21, 16, v82
	v_add_f32_e32 v12, v12, v13
	v_mul_f32_e32 v13, v22, v22
	v_and_b32_e32 v25, 0xffff0000, v83
	v_fmac_f32_e32 v13, v21, v21
	v_lshlrev_b32_e32 v23, 16, v83
	v_add_f32_e32 v12, v13, v12
	v_mul_f32_e32 v13, v25, v25
	v_fmac_f32_e32 v13, v23, v23
	v_add_f32_e32 v12, v13, v12
	v_add_f32_e32 v24, v24, v12
	s_waitcnt vmcnt(3)
	v_lshlrev_b32_e32 v26, 16, v84
	v_and_b32_e32 v12, 0xffff0000, v84
	v_mul_f32_e32 v12, v18, v12
	v_fmac_f32_e32 v12, v17, v26
	v_lshlrev_b32_e32 v17, 16, v85
	v_and_b32_e32 v13, 0xffff0000, v85
	v_mul_f32_e32 v13, v20, v13
	v_fmac_f32_e32 v13, v19, v17
	v_add_f32_e32 v12, v12, v13
	v_lshlrev_b32_e32 v13, 16, v86
	v_and_b32_e32 v14, 0xffff0000, v86
	v_mul_f32_e32 v14, v22, v14
	v_fmac_f32_e32 v14, v21, v13
	v_add_f32_e32 v12, v14, v12
	v_and_b32_e32 v14, 0xffff0000, v87
	v_lshlrev_b32_e32 v13, 16, v87
	v_mul_f32_e32 v14, v25, v14
	v_fmac_f32_e32 v14, v23, v13
	v_add_f32_e32 v12, v14, v12
	v_add_f32_e32 v16, v16, v12
	s_waitcnt vmcnt(2)
	v_lshlrev_b32_e32 v17, 16, v88
	v_and_b32_e32 v12, 0xffff0000, v88
	v_lshlrev_b32_e32 v18, 16, v89
	v_and_b32_e32 v13, 0xffff0000, v89
	v_mul_f32_e32 v8, v12, v12
	v_mul_f32_e32 v9, v13, v13
	v_lshlrev_b32_e32 v19, 16, v90
	v_and_b32_e32 v14, 0xffff0000, v90
	v_fmac_f32_e32 v8, v17, v17
	v_fmac_f32_e32 v9, v18, v18
	v_add_f32_e32 v8, v8, v9
	v_mul_f32_e32 v9, v14, v14
	v_lshlrev_b32_e32 v20, 16, v91
	v_and_b32_e32 v15, 0xffff0000, v91
	v_fmac_f32_e32 v9, v19, v19
	v_add_f32_e32 v8, v9, v8
	v_mul_f32_e32 v9, v15, v15
	v_fmac_f32_e32 v9, v20, v20
	v_add_f32_e32 v8, v9, v8
	v_add_f32_e32 v21, v24, v8
	s_waitcnt vmcnt(1)
; __device__ __forceinline__ float bflo(unsigned w) { return __uint_as_float(w << 16); }
; __device__ __forceinline__ float bfhi(unsigned w) { return __uint_as_float(w & 0xffff0000u); }
; __device__ __forceinline__ float sq8(const v4u w) { const float a0 = bflo(w.x), a1 = bfhi(w.x), a2 = bflo(w.y), a3 = bfhi(w.y), a4 = bflo(w.z), a5 = bfhi(w.z), a6 = bflo(w.w), a7 = bfhi(w.w); return (a0 * a0 + a1 * a1) + (a2 * a2 + a3 * a3) + (a4 * a4 + a5 * a5) + (a6 * a6 + a7 * a7); }
; __device__ __forceinline__ float dot8(const v4u a, const v4u b) { return (bflo(a.x) * bflo(b.x) + bfhi(a.x) * bfhi(b.x)) + (bflo(a.y) * bflo(b.y) + bfhi(a.y) * bfhi(b.y)) + (bflo(a.z) * bflo(b.z) + bfhi(a.z) * bfhi(b.z)) + (bflo(a.w) * bflo(b.w) + bfhi(a.w) * bfhi(b.w)); }
; __device__ __forceinline__ void fox_bounds(Frame& F) {
;     ...
;             for (int r = 0; r < 4; ++r) { const int i = qb * 256 + F.lane + 64 * r; const size_t row = (size_t)b * SEQ + i;
;                 const v4u* qp = (const v4u*)(QO + row * DM + 512 + h * 64); const v4u* kp = (const v4u*)(FK + row * 512 + h * 64); float qq = 0.f, qk = 0.f;
; #pragma unroll
;                 for (int d8 = 0; d8 < 8; ++d8) { const v4u qv = qp[d8]; qq += sq8(qv); qk += dot8(qv, kp[d8]); }
;                 q2 = fmaxf(q2, qq); sm = fminf(sm, qk - C2[(size_t)bh * SEQ + i]); }
	v_lshlrev_b32_e32 v22, 16, v92
	v_and_b32_e32 v6, 0xffff0000, v92
	v_mul_f32_e32 v6, v12, v6
	v_lshlrev_b32_e32 v12, 16, v93
	v_and_b32_e32 v7, 0xffff0000, v93
	v_mul_f32_e32 v7, v13, v7
	v_fmac_f32_e32 v6, v17, v22
	v_fmac_f32_e32 v7, v18, v12
	v_add_f32_e32 v6, v6, v7
	v_lshlrev_b32_e32 v7, 16, v94
	v_and_b32_e32 v8, 0xffff0000, v94
	v_mul_f32_e32 v8, v14, v8
	v_fmac_f32_e32 v8, v19, v7
	v_add_f32_e32 v6, v8, v6
	v_and_b32_e32 v8, 0xffff0000, v95
	v_lshlrev_b32_e32 v7, 16, v95
	v_mul_f32_e32 v8, v15, v8
	v_fmac_f32_e32 v8, v20, v7
	v_add_f32_e32 v6, v8, v6
	v_add_f32_e32 v6, v16, v6
	v_max3_f32 v12, v11, 0, v21
	s_waitcnt vmcnt(0)
	v_mov_b32_e32 v7, v96
	v_mov_b32_e32 v9, v95
	v_sub_f32_e32 v11, v6, v7
	v_or_b32_e32 v6, 0x80, v0
	v_mov_b32_e32 v7, v1
	v_lshlrev_b64 v[8:9], 11, v[6:7]
	v_lshl_add_u64 v[8:9], s[10:11], 0, v[8:9]
	v_lshl_add_u64 v[14:15], v[8:9], 0, s[68:69]
	v_lshl_add_u64 v[8:9], v[14:15], 0, s[38:39]
	v_add_co_u32_e32 v14, vcc, s2, v14
	v_lshlrev_b64 v[6:7], 10, v[6:7]
	s_nop 0
	v_addc_co_u32_e32 v15, vcc, 0, v15, vcc
	v_lshl_add_u64 v[6:7], s[6:7], 0, v[6:7]
	v_or_b32_e32 v0, 0xc0, v0
	v_max3_f32 v10, -v10, s40, -v11
	global_load_dwordx4 v[32:35], v[14:15], off offset:1024
	global_load_dwordx4 v[36:39], v[6:7], off
	global_load_dwordx4 v[40:43], v[8:9], off offset:16
	global_load_dwordx4 v[44:47], v[6:7], off offset:16
	global_load_dwordx4 v[48:51], v[8:9], off offset:32
	global_load_dwordx4 v[52:55], v[6:7], off offset:32
	global_load_dwordx4 v[56:59], v[8:9], off offset:48
	global_load_dwordx4 v[60:63], v[6:7], off offset:48
	global_load_dwordx4 v[64:67], v[8:9], off offset:64
	global_load_dwordx4 v[68:71], v[6:7], off offset:64
	global_load_dwordx4 v[72:75], v[8:9], off offset:80
	global_load_dwordx4 v[76:79], v[6:7], off offset:80
	global_load_dwordx4 v[80:83], v[8:9], off offset:96
	global_load_dwordx4 v[84:87], v[6:7], off offset:96
	global_load_dwordx4 v[88:91], v[8:9], off offset:112
	global_load_dwordx4 v[92:95], v[6:7], off offset:112
	global_load_dword v96, v[2:3], off offset:512
	global_load_dword v97, v[2:3], off offset:768
	s_waitcnt vmcnt(17)
	v_and_b32_e32 v18, 0xffff0000, v32
	v_and_b32_e32 v20, 0xffff0000, v33
	v_lshlrev_b32_e32 v13, 16, v32
	v_lshlrev_b32_e32 v19, 16, v33
	v_mul_f32_e32 v14, v18, v18
	v_mul_f32_e32 v15, v20, v20
	v_and_b32_e32 v22, 0xffff0000, v34
	v_fmac_f32_e32 v14, v13, v13
	v_fmac_f32_e32 v15, v19, v19
	v_lshlrev_b32_e32 v21, 16, v34
	v_add_f32_e32 v14, v14, v15
	v_mul_f32_e32 v15, v22, v22
	v_and_b32_e32 v24, 0xffff0000, v35
	v_fmac_f32_e32 v15, v21, v21
	v_lshlrev_b32_e32 v23, 16, v35
	v_add_f32_e32 v14, v15, v14
	v_mul_f32_e32 v15, v24, v24
	v_fmac_f32_e32 v15, v23, v23
	v_add_f32_e32 v25, v15, v14
	s_waitcnt vmcnt(16)
	v_lshlrev_b32_e32 v26, 16, v36
	v_and_b32_e32 v14, 0xffff0000, v36
	v_mul_f32_e32 v14, v18, v14
	v_fmac_f32_e32 v14, v13, v26
	v_lshlrev_b32_e32 v13, 16, v37
	v_and_b32_e32 v15, 0xffff0000, v37
	v_mul_f32_e32 v15, v20, v15
	v_fmac_f32_e32 v15, v19, v13
	v_add_f32_e32 v13, v14, v15
	v_and_b32_e32 v15, 0xffff0000, v38
	v_lshlrev_b32_e32 v14, 16, v38
	v_mul_f32_e32 v15, v22, v15
	v_fmac_f32_e32 v15, v21, v14
	v_add_f32_e32 v13, v15, v13
	v_and_b32_e32 v15, 0xffff0000, v39
	v_lshlrev_b32_e32 v14, 16, v39
	v_mul_f32_e32 v15, v24, v15
	v_fmac_f32_e32 v15, v23, v14
	v_add_f32_e32 v13, v15, v13
	v_add_f32_e32 v13, 0, v13
	s_waitcnt vmcnt(15)
	v_and_b32_e32 v19, 0xffff0000, v40
	v_and_b32_e32 v21, 0xffff0000, v41
	v_lshlrev_b32_e32 v18, 16, v40
	v_lshlrev_b32_e32 v20, 16, v41
	v_mul_f32_e32 v14, v19, v19
	v_mul_f32_e32 v15, v21, v21
	v_and_b32_e32 v23, 0xffff0000, v42
	v_fmac_f32_e32 v14, v18, v18
	v_fmac_f32_e32 v15, v20, v20
	v_lshlrev_b32_e32 v22, 16, v42
	v_add_f32_e32 v14, v14, v15
	v_mul_f32_e32 v15, v23, v23
	v_and_b32_e32 v26, 0xffff0000, v43
	v_fmac_f32_e32 v15, v22, v22
	v_lshlrev_b32_e32 v24, 16, v43
	v_add_f32_e32 v14, v15, v14
	v_mul_f32_e32 v15, v26, v26
	v_fmac_f32_e32 v15, v24, v24
	v_add_f32_e32 v14, v15, v14
	v_add_f32_e32 v25, v25, v14
	s_waitcnt vmcnt(14)
	v_lshlrev_b32_e32 v27, 16, v44
	v_and_b32_e32 v14, 0xffff0000, v44
	v_mul_f32_e32 v14, v19, v14
	v_fmac_f32_e32 v14, v18, v27
	v_lshlrev_b32_e32 v18, 16, v45
	v_and_b32_e32 v15, 0xffff0000, v45
	v_mul_f32_e32 v15, v21, v15
	v_fmac_f32_e32 v15, v20, v18
	v_add_f32_e32 v14, v14, v15
	v_lshlrev_b32_e32 v15, 16, v46
	v_and_b32_e32 v16, 0xffff0000, v46
	v_mul_f32_e32 v16, v23, v16
	v_fmac_f32_e32 v16, v22, v15
	v_add_f32_e32 v14, v16, v14
	v_and_b32_e32 v16, 0xffff0000, v47
	v_lshlrev_b32_e32 v15, 16, v47
	v_mul_f32_e32 v16, v26, v16
	v_fmac_f32_e32 v16, v24, v15
	v_add_f32_e32 v14, v16, v14
	v_add_f32_e32 v13, v13, v14
	s_waitcnt vmcnt(13)
	v_and_b32_e32 v19, 0xffff0000, v48
	v_and_b32_e32 v21, 0xffff0000, v49
	v_lshlrev_b32_e32 v18, 16, v48
	v_lshlrev_b32_e32 v20, 16, v49
	v_mul_f32_e32 v14, v19, v19
	v_mul_f32_e32 v15, v21, v21
	v_and_b32_e32 v23, 0xffff0000, v50
	v_fmac_f32_e32 v14, v18, v18
	v_fmac_f32_e32 v15, v20, v20
	v_lshlrev_b32_e32 v22, 16, v50
	v_add_f32_e32 v14, v14, v15
	v_mul_f32_e32 v15, v23, v23
	v_and_b32_e32 v26, 0xffff0000, v51
	v_fmac_f32_e32 v15, v22, v22
	v_lshlrev_b32_e32 v24, 16, v51
	v_add_f32_e32 v14, v15, v14
	v_mul_f32_e32 v15, v26, v26
	v_fmac_f32_e32 v15, v24, v24
	v_add_f32_e32 v14, v15, v14
	v_add_f32_e32 v25, v25, v14
	s_waitcnt vmcnt(12)
	v_lshlrev_b32_e32 v27, 16, v52
	v_and_b32_e32 v14, 0xffff0000, v52
	v_mul_f32_e32 v14, v19, v14
	v_fmac_f32_e32 v14, v18, v27
	v_lshlrev_b32_e32 v18, 16, v53
	v_and_b32_e32 v15, 0xffff0000, v53
	v_mul_f32_e32 v15, v21, v15
	v_fmac_f32_e32 v15, v20, v18
	v_add_f32_e32 v14, v14, v15
	v_lshlrev_b32_e32 v15, 16, v54
	v_and_b32_e32 v16, 0xffff0000, v54
	v_mul_f32_e32 v16, v23, v16
	v_fmac_f32_e32 v16, v22, v15
	v_add_f32_e32 v14, v16, v14
	v_and_b32_e32 v16, 0xffff0000, v55
	v_lshlrev_b32_e32 v15, 16, v55
	v_mul_f32_e32 v16, v26, v16
	v_fmac_f32_e32 v16, v24, v15
	v_add_f32_e32 v14, v16, v14
	v_add_f32_e32 v13, v13, v14
	s_waitcnt vmcnt(11)
; __device__ __forceinline__ float bflo(unsigned w) { return __uint_as_float(w << 16); }
; __device__ __forceinline__ float bfhi(unsigned w) { return __uint_as_float(w & 0xffff0000u); }
; __device__ __forceinline__ float sq8(const v4u w) { const float a0 = bflo(w.x), a1 = bfhi(w.x), a2 = bflo(w.y), a3 = bfhi(w.y), a4 = bflo(w.z), a5 = bfhi(w.z), a6 = bflo(w.w), a7 = bfhi(w.w); return (a0 * a0 + a1 * a1) + (a2 * a2 + a3 * a3) + (a4 * a4 + a5 * a5) + (a6 * a6 + a7 * a7); }
; __device__ __forceinline__ float dot8(const v4u a, const v4u b) { return (bflo(a.x) * bflo(b.x) + bfhi(a.x) * bfhi(b.x)) + (bflo(a.y) * bflo(b.y) + bfhi(a.y) * bfhi(b.y)) + (bflo(a.z) * bflo(b.z) + bfhi(a.z) * bfhi(b.z)) + (bflo(a.w) * bflo(b.w) + bfhi(a.w) * bfhi(b.w)); }
; __device__ __forceinline__ void fox_bounds(Frame& F) {
;     ...
;             for (int r = 0; r < 4; ++r) { const int i = qb * 256 + F.lane + 64 * r; const size_t row = (size_t)b * SEQ + i;
;                 const v4u* qp = (const v4u*)(QO + row * DM + 512 + h * 64); const v4u* kp = (const v4u*)(FK + row * 512 + h * 64); float qq = 0.f, qk = 0.f;
; #pragma unroll
;                 for (int d8 = 0; d8 < 8; ++d8) { const v4u qv = qp[d8]; qq += sq8(qv); qk += dot8(qv, kp[d8]); }
	v_and_b32_e32 v19, 0xffff0000, v56
	v_and_b32_e32 v21, 0xffff0000, v57
	v_lshlrev_b32_e32 v18, 16, v56
	v_lshlrev_b32_e32 v20, 16, v57
	v_mul_f32_e32 v14, v19, v19
	v_mul_f32_e32 v15, v21, v21
	v_and_b32_e32 v23, 0xffff0000, v58
	v_fmac_f32_e32 v14, v18, v18
	v_fmac_f32_e32 v15, v20, v20
	v_lshlrev_b32_e32 v22, 16, v58
	v_add_f32_e32 v14, v14, v15
	v_mul_f32_e32 v15, v23, v23
	v_and_b32_e32 v26, 0xffff0000, v59
	v_fmac_f32_e32 v15, v22, v22
	v_lshlrev_b32_e32 v24, 16, v59
	v_add_f32_e32 v14, v15, v14
	v_mul_f32_e32 v15, v26, v26
	v_fmac_f32_e32 v15, v24, v24
	v_add_f32_e32 v14, v15, v14
	v_add_f32_e32 v25, v25, v14
	s_waitcnt vmcnt(10)
	v_lshlrev_b32_e32 v27, 16, v60
	v_and_b32_e32 v14, 0xffff0000, v60
	v_mul_f32_e32 v14, v19, v14
	v_fmac_f32_e32 v14, v18, v27
	v_lshlrev_b32_e32 v18, 16, v61
	v_and_b32_e32 v15, 0xffff0000, v61
	v_mul_f32_e32 v15, v21, v15
	v_fmac_f32_e32 v15, v20, v18
	v_add_f32_e32 v14, v14, v15
	v_lshlrev_b32_e32 v15, 16, v62
	v_and_b32_e32 v16, 0xffff0000, v62
	v_mul_f32_e32 v16, v23, v16
	v_fmac_f32_e32 v16, v22, v15
	v_add_f32_e32 v14, v16, v14
	v_and_b32_e32 v16, 0xffff0000, v63
	v_lshlrev_b32_e32 v15, 16, v63
	v_mul_f32_e32 v16, v26, v16
	v_fmac_f32_e32 v16, v24, v15
	v_add_f32_e32 v14, v16, v14
	v_add_f32_e32 v13, v13, v14
	s_waitcnt vmcnt(9)
	v_and_b32_e32 v19, 0xffff0000, v64
	v_and_b32_e32 v21, 0xffff0000, v65
	v_lshlrev_b32_e32 v18, 16, v64
	v_lshlrev_b32_e32 v20, 16, v65
	v_mul_f32_e32 v14, v19, v19
	v_mul_f32_e32 v15, v21, v21
	v_and_b32_e32 v23, 0xffff0000, v66
	v_fmac_f32_e32 v14, v18, v18
	v_fmac_f32_e32 v15, v20, v20
	v_lshlrev_b32_e32 v22, 16, v66
	v_add_f32_e32 v14, v14, v15
	v_mul_f32_e32 v15, v23, v23
	v_and_b32_e32 v26, 0xffff0000, v67
	v_fmac_f32_e32 v15, v22, v22
	v_lshlrev_b32_e32 v24, 16, v67
	v_add_f32_e32 v14, v15, v14
	v_mul_f32_e32 v15, v26, v26
	v_fmac_f32_e32 v15, v24, v24
	v_add_f32_e32 v14, v15, v14
	v_add_f32_e32 v25, v25, v14
	s_waitcnt vmcnt(8)
	v_lshlrev_b32_e32 v27, 16, v68
	v_and_b32_e32 v14, 0xffff0000, v68
	v_mul_f32_e32 v14, v19, v14
	v_fmac_f32_e32 v14, v18, v27
	v_lshlrev_b32_e32 v18, 16, v69
	v_and_b32_e32 v15, 0xffff0000, v69
	v_mul_f32_e32 v15, v21, v15
	v_fmac_f32_e32 v15, v20, v18
	v_add_f32_e32 v14, v14, v15
	v_lshlrev_b32_e32 v15, 16, v70
	v_and_b32_e32 v16, 0xffff0000, v70
	v_mul_f32_e32 v16, v23, v16
	v_fmac_f32_e32 v16, v22, v15
	v_add_f32_e32 v14, v16, v14
	v_and_b32_e32 v16, 0xffff0000, v71
	v_lshlrev_b32_e32 v15, 16, v71
	v_mul_f32_e32 v16, v26, v16
	v_fmac_f32_e32 v16, v24, v15
	v_add_f32_e32 v14, v16, v14
	v_add_f32_e32 v13, v13, v14
	s_waitcnt vmcnt(7)
	v_and_b32_e32 v19, 0xffff0000, v72
	v_and_b32_e32 v21, 0xffff0000, v73
	v_lshlrev_b32_e32 v18, 16, v72
	v_lshlrev_b32_e32 v20, 16, v73
	v_mul_f32_e32 v14, v19, v19
	v_mul_f32_e32 v15, v21, v21
	v_and_b32_e32 v23, 0xffff0000, v74
	v_fmac_f32_e32 v14, v18, v18
	v_fmac_f32_e32 v15, v20, v20
	v_lshlrev_b32_e32 v22, 16, v74
	v_add_f32_e32 v14, v14, v15
	v_mul_f32_e32 v15, v23, v23
	v_and_b32_e32 v26, 0xffff0000, v75
	v_fmac_f32_e32 v15, v22, v22
	v_lshlrev_b32_e32 v24, 16, v75
	v_add_f32_e32 v14, v15, v14
	v_mul_f32_e32 v15, v26, v26
	v_fmac_f32_e32 v15, v24, v24
	v_add_f32_e32 v14, v15, v14
	v_add_f32_e32 v25, v25, v14
	s_waitcnt vmcnt(6)
	v_lshlrev_b32_e32 v27, 16, v76
	v_and_b32_e32 v14, 0xffff0000, v76
	v_mul_f32_e32 v14, v19, v14
	v_fmac_f32_e32 v14, v18, v27
	v_lshlrev_b32_e32 v18, 16, v77
	v_and_b32_e32 v15, 0xffff0000, v77
	v_mul_f32_e32 v15, v21, v15
	v_fmac_f32_e32 v15, v20, v18
	v_add_f32_e32 v14, v14, v15
	v_lshlrev_b32_e32 v15, 16, v78
	v_and_b32_e32 v16, 0xffff0000, v78
	v_mul_f32_e32 v16, v23, v16
	v_fmac_f32_e32 v16, v22, v15
	v_add_f32_e32 v14, v16, v14
	v_and_b32_e32 v16, 0xffff0000, v79
	v_lshlrev_b32_e32 v15, 16, v79
	v_mul_f32_e32 v16, v26, v16
	v_fmac_f32_e32 v16, v24, v15
	v_add_f32_e32 v14, v16, v14
	v_add_f32_e32 v13, v13, v14
	s_waitcnt vmcnt(5)
	v_and_b32_e32 v19, 0xffff0000, v80
	v_and_b32_e32 v21, 0xffff0000, v81
	v_lshlrev_b32_e32 v18, 16, v80
	v_lshlrev_b32_e32 v20, 16, v81
	v_mul_f32_e32 v14, v19, v19
	v_mul_f32_e32 v15, v21, v21
	v_and_b32_e32 v23, 0xffff0000, v82
	v_fmac_f32_e32 v14, v18, v18
	v_fmac_f32_e32 v15, v20, v20
	v_lshlrev_b32_e32 v22, 16, v82
	v_add_f32_e32 v14, v14, v15
	v_mul_f32_e32 v15, v23, v23
	v_and_b32_e32 v26, 0xffff0000, v83
	v_fmac_f32_e32 v15, v22, v22
	v_lshlrev_b32_e32 v24, 16, v83
	v_add_f32_e32 v14, v15, v14
	v_mul_f32_e32 v15, v26, v26
	v_fmac_f32_e32 v15, v24, v24
	v_add_f32_e32 v14, v15, v14
	v_add_f32_e32 v25, v25, v14
	s_waitcnt vmcnt(4)
	v_lshlrev_b32_e32 v27, 16, v84
	v_and_b32_e32 v14, 0xffff0000, v84
	v_mul_f32_e32 v14, v19, v14
	v_fmac_f32_e32 v14, v18, v27
	v_lshlrev_b32_e32 v18, 16, v85
	v_and_b32_e32 v15, 0xffff0000, v85
	v_mul_f32_e32 v15, v21, v15
	v_fmac_f32_e32 v15, v20, v18
	v_add_f32_e32 v14, v14, v15
	v_lshlrev_b32_e32 v15, 16, v86
	v_and_b32_e32 v16, 0xffff0000, v86
	v_mul_f32_e32 v16, v23, v16
	v_fmac_f32_e32 v16, v22, v15
	v_add_f32_e32 v14, v16, v14
	v_and_b32_e32 v16, 0xffff0000, v87
	v_lshlrev_b32_e32 v15, 16, v87
	v_mul_f32_e32 v16, v26, v16
	v_fmac_f32_e32 v16, v24, v15
	v_add_f32_e32 v14, v16, v14
	v_add_f32_e32 v13, v13, v14
	s_waitcnt vmcnt(3)
	v_and_b32_e32 v18, 0xffff0000, v88
	v_and_b32_e32 v20, 0xffff0000, v89
	v_lshlrev_b32_e32 v8, 16, v88
	v_lshlrev_b32_e32 v19, 16, v89
	v_mul_f32_e32 v9, v18, v18
	v_mul_f32_e32 v14, v20, v20
	v_and_b32_e32 v22, 0xffff0000, v90
	v_fmac_f32_e32 v9, v8, v8
	v_fmac_f32_e32 v14, v19, v19
	v_lshlrev_b32_e32 v21, 16, v90
	v_add_f32_e32 v9, v9, v14
	v_mul_f32_e32 v14, v22, v22
	v_and_b32_e32 v24, 0xffff0000, v91
	v_fmac_f32_e32 v14, v21, v21
	v_lshlrev_b32_e32 v23, 16, v91
	v_add_f32_e32 v9, v14, v9
	v_mul_f32_e32 v14, v24, v24
	v_fmac_f32_e32 v14, v23, v23
	v_add_f32_e32 v9, v14, v9
	v_add_f32_e32 v9, v25, v9
	s_waitcnt vmcnt(2)
; __device__ __forceinline__ float bflo(unsigned w) { return __uint_as_float(w << 16); }
; __device__ __forceinline__ float bfhi(unsigned w) { return __uint_as_float(w & 0xffff0000u); }
; __device__ __forceinline__ float sq8(const v4u w) { const float a0 = bflo(w.x), a1 = bfhi(w.x), a2 = bflo(w.y), a3 = bfhi(w.y), a4 = bflo(w.z), a5 = bfhi(w.z), a6 = bflo(w.w), a7 = bfhi(w.w); return (a0 * a0 + a1 * a1) + (a2 * a2 + a3 * a3) + (a4 * a4 + a5 * a5) + (a6 * a6 + a7 * a7); }
; __device__ __forceinline__ float dot8(const v4u a, const v4u b) { return (bflo(a.x) * bflo(b.x) + bfhi(a.x) * bfhi(b.x)) + (bflo(a.y) * bflo(b.y) + bfhi(a.y) * bfhi(b.y)) + (bflo(a.z) * bflo(b.z) + bfhi(a.z) * bfhi(b.z)) + (bflo(a.w) * bflo(b.w) + bfhi(a.w) * bfhi(b.w)); }
; __device__ __forceinline__ void fox_bounds(Frame& F) {
;     ...
;             for (int r = 0; r < 4; ++r) { const int i = qb * 256 + F.lane + 64 * r; const size_t row = (size_t)b * SEQ + i;
;                 const v4u* qp = (const v4u*)(QO + row * DM + 512 + h * 64); const v4u* kp = (const v4u*)(FK + row * 512 + h * 64); float qq = 0.f, qk = 0.f;
; #pragma unroll
;                 for (int d8 = 0; d8 < 8; ++d8) { const v4u qv = qp[d8]; qq += sq8(qv); qk += dot8(qv, kp[d8]); }
;                 q2 = fmaxf(q2, qq); sm = fminf(sm, qk - C2[(size_t)bh * SEQ + i]); }
	v_and_b32_e32 v7, 0xffff0000, v92
	v_lshlrev_b32_e32 v6, 16, v92
	v_mul_f32_e32 v7, v18, v7
	v_fmac_f32_e32 v7, v8, v6
	v_and_b32_e32 v8, 0xffff0000, v93
	v_lshlrev_b32_e32 v6, 16, v93
	v_mul_f32_e32 v8, v20, v8
	v_fmac_f32_e32 v8, v19, v6
	v_add_f32_e32 v6, v7, v8
	v_and_b32_e32 v8, 0xffff0000, v94
	v_lshlrev_b32_e32 v7, 16, v94
	v_mul_f32_e32 v8, v22, v8
	v_fmac_f32_e32 v8, v21, v7
	v_add_f32_e32 v6, v8, v6
	v_and_b32_e32 v8, 0xffff0000, v95
	v_lshlrev_b32_e32 v7, 16, v95
	v_mul_f32_e32 v8, v24, v8
	v_fmac_f32_e32 v8, v23, v7
	v_add_f32_e32 v6, v8, v6
	v_add_f32_e32 v6, v13, v6
	s_waitcnt vmcnt(1)
	s_waitcnt vmcnt(0)
	v_xor_b32_e32 v3, 1, v215
	v_mov_b32_e32 v2, v97
	v_mov_b32_e32 v7, v96
	v_mov_b32_e32 v14, v92
	v_mov_b32_e32 v15, v93
	v_mov_b32_e32 v16, v94
	v_mov_b32_e32 v17, v95
	v_sub_f32_e32 v8, v6, v7
	v_lshlrev_b64 v[6:7], 11, v[0:1]
	v_lshl_add_u64 v[6:7], s[10:11], 0, v[6:7]
	v_lshl_add_u64 v[14:15], v[6:7], 0, s[68:69]
	v_lshl_add_u64 v[6:7], v[14:15], 0, s[38:39]
	v_add_co_u32_e32 v14, vcc, s2, v14
	v_lshlrev_b64 v[0:1], 10, v[0:1]
	s_nop 0
	v_addc_co_u32_e32 v15, vcc, 0, v15, vcc
	v_lshl_add_u64 v[0:1], s[6:7], 0, v[0:1]
	global_load_dwordx4 v[32:35], v[14:15], off offset:1024
	global_load_dwordx4 v[36:39], v[0:1], off
	global_load_dwordx4 v[40:43], v[6:7], off offset:16
	global_load_dwordx4 v[44:47], v[0:1], off offset:16
	global_load_dwordx4 v[48:51], v[6:7], off offset:32
	global_load_dwordx4 v[52:55], v[0:1], off offset:32
	global_load_dwordx4 v[56:59], v[6:7], off offset:48
	global_load_dwordx4 v[60:63], v[0:1], off offset:48
	global_load_dwordx4 v[64:67], v[6:7], off offset:64
	global_load_dwordx4 v[68:71], v[0:1], off offset:64
	global_load_dwordx4 v[72:75], v[6:7], off offset:80
	global_load_dwordx4 v[76:79], v[0:1], off offset:80
	global_load_dwordx4 v[80:83], v[6:7], off offset:96
	global_load_dwordx4 v[84:87], v[0:1], off offset:96
	global_load_dwordx4 v[88:91], v[6:7], off offset:112
	global_load_dwordx4 v[92:95], v[0:1], off offset:112
	s_waitcnt vmcnt(15)
	v_and_b32_e32 v18, 0xffff0000, v32
	v_and_b32_e32 v20, 0xffff0000, v33
	v_lshlrev_b32_e32 v13, 16, v32
	v_lshlrev_b32_e32 v19, 16, v33
	v_mul_f32_e32 v14, v18, v18
	v_mul_f32_e32 v15, v20, v20
	v_and_b32_e32 v22, 0xffff0000, v34
	v_fmac_f32_e32 v14, v13, v13
	v_fmac_f32_e32 v15, v19, v19
	v_lshlrev_b32_e32 v21, 16, v34
	v_add_f32_e32 v14, v14, v15
	v_mul_f32_e32 v15, v22, v22
	v_and_b32_e32 v24, 0xffff0000, v35
	v_fmac_f32_e32 v15, v21, v21
	v_lshlrev_b32_e32 v23, 16, v35
	v_add_f32_e32 v14, v15, v14
	v_mul_f32_e32 v15, v24, v24
	v_fmac_f32_e32 v15, v23, v23
	v_add_f32_e32 v25, v15, v14
	s_waitcnt vmcnt(14)
	v_lshlrev_b32_e32 v26, 16, v36
	v_and_b32_e32 v14, 0xffff0000, v36
	v_mul_f32_e32 v14, v18, v14
	v_fmac_f32_e32 v14, v13, v26
	v_lshlrev_b32_e32 v13, 16, v37
	v_and_b32_e32 v15, 0xffff0000, v37
	v_mul_f32_e32 v15, v20, v15
	v_fmac_f32_e32 v15, v19, v13
	v_add_f32_e32 v13, v14, v15
	v_and_b32_e32 v15, 0xffff0000, v38
	v_lshlrev_b32_e32 v14, 16, v38
	v_mul_f32_e32 v15, v22, v15
	v_fmac_f32_e32 v15, v21, v14
	v_add_f32_e32 v13, v15, v13
	v_and_b32_e32 v15, 0xffff0000, v39
	v_lshlrev_b32_e32 v14, 16, v39
	v_mul_f32_e32 v15, v24, v15
	v_fmac_f32_e32 v15, v23, v14
	v_add_f32_e32 v13, v15, v13
	v_add_f32_e32 v13, 0, v13
	s_waitcnt vmcnt(13)
	v_and_b32_e32 v19, 0xffff0000, v40
	v_and_b32_e32 v21, 0xffff0000, v41
	v_lshlrev_b32_e32 v18, 16, v40
	v_lshlrev_b32_e32 v20, 16, v41
	v_mul_f32_e32 v14, v19, v19
	v_mul_f32_e32 v15, v21, v21
	v_and_b32_e32 v23, 0xffff0000, v42
	v_fmac_f32_e32 v14, v18, v18
	v_fmac_f32_e32 v15, v20, v20
	v_lshlrev_b32_e32 v22, 16, v42
	v_add_f32_e32 v14, v14, v15
	v_mul_f32_e32 v15, v23, v23
	v_and_b32_e32 v26, 0xffff0000, v43
	v_fmac_f32_e32 v15, v22, v22
	v_lshlrev_b32_e32 v24, 16, v43
	v_add_f32_e32 v14, v15, v14
	v_mul_f32_e32 v15, v26, v26
	v_fmac_f32_e32 v15, v24, v24
	v_add_f32_e32 v14, v15, v14
	v_add_f32_e32 v25, v25, v14
	s_waitcnt vmcnt(12)
	v_lshlrev_b32_e32 v27, 16, v44
	v_and_b32_e32 v14, 0xffff0000, v44
	v_mul_f32_e32 v14, v19, v14
	v_fmac_f32_e32 v14, v18, v27
	v_lshlrev_b32_e32 v18, 16, v45
	v_and_b32_e32 v15, 0xffff0000, v45
	v_mul_f32_e32 v15, v21, v15
	v_fmac_f32_e32 v15, v20, v18
	v_add_f32_e32 v14, v14, v15
	v_lshlrev_b32_e32 v15, 16, v46
	v_and_b32_e32 v16, 0xffff0000, v46
	v_mul_f32_e32 v16, v23, v16
	v_fmac_f32_e32 v16, v22, v15
	v_add_f32_e32 v14, v16, v14
	v_and_b32_e32 v16, 0xffff0000, v47
	v_lshlrev_b32_e32 v15, 16, v47
	v_mul_f32_e32 v16, v26, v16
	v_fmac_f32_e32 v16, v24, v15
	v_add_f32_e32 v14, v16, v14
	v_add_f32_e32 v13, v13, v14
	s_waitcnt vmcnt(11)
	v_and_b32_e32 v19, 0xffff0000, v48
	v_and_b32_e32 v21, 0xffff0000, v49
	v_lshlrev_b32_e32 v18, 16, v48
	v_lshlrev_b32_e32 v20, 16, v49
	v_mul_f32_e32 v14, v19, v19
	v_mul_f32_e32 v15, v21, v21
	v_and_b32_e32 v23, 0xffff0000, v50
	v_fmac_f32_e32 v14, v18, v18
	v_fmac_f32_e32 v15, v20, v20
	v_lshlrev_b32_e32 v22, 16, v50
	v_add_f32_e32 v14, v14, v15
	v_mul_f32_e32 v15, v23, v23
	v_and_b32_e32 v26, 0xffff0000, v51
	v_fmac_f32_e32 v15, v22, v22
	v_lshlrev_b32_e32 v24, 16, v51
	v_add_f32_e32 v14, v15, v14
	v_mul_f32_e32 v15, v26, v26
	v_fmac_f32_e32 v15, v24, v24
	v_add_f32_e32 v14, v15, v14
	v_add_f32_e32 v25, v25, v14
	s_waitcnt vmcnt(10)
	v_lshlrev_b32_e32 v27, 16, v52
	v_and_b32_e32 v14, 0xffff0000, v52
	v_mul_f32_e32 v14, v19, v14
	v_fmac_f32_e32 v14, v18, v27
	v_lshlrev_b32_e32 v18, 16, v53
	v_and_b32_e32 v15, 0xffff0000, v53
	v_mul_f32_e32 v15, v21, v15
	v_fmac_f32_e32 v15, v20, v18
	v_add_f32_e32 v14, v14, v15
	v_lshlrev_b32_e32 v15, 16, v54
	v_and_b32_e32 v16, 0xffff0000, v54
	v_mul_f32_e32 v16, v23, v16
	v_fmac_f32_e32 v16, v22, v15
	v_add_f32_e32 v14, v16, v14
	v_and_b32_e32 v16, 0xffff0000, v55
	v_lshlrev_b32_e32 v15, 16, v55
	v_mul_f32_e32 v16, v26, v16
	v_fmac_f32_e32 v16, v24, v15
	v_add_f32_e32 v14, v16, v14
	v_add_f32_e32 v13, v13, v14
	s_waitcnt vmcnt(9)
; __device__ __forceinline__ float bflo(unsigned w) { return __uint_as_float(w << 16); }
; __device__ __forceinline__ float bfhi(unsigned w) { return __uint_as_float(w & 0xffff0000u); }
; __device__ __forceinline__ float sq8(const v4u w) { const float a0 = bflo(w.x), a1 = bfhi(w.x), a2 = bflo(w.y), a3 = bfhi(w.y), a4 = bflo(w.z), a5 = bfhi(w.z), a6 = bflo(w.w), a7 = bfhi(w.w); return (a0 * a0 + a1 * a1) + (a2 * a2 + a3 * a3) + (a4 * a4 + a5 * a5) + (a6 * a6 + a7 * a7); }
; __device__ __forceinline__ float dot8(const v4u a, const v4u b) { return (bflo(a.x) * bflo(b.x) + bfhi(a.x) * bfhi(b.x)) + (bflo(a.y) * bflo(b.y) + bfhi(a.y) * bfhi(b.y)) + (bflo(a.z) * bflo(b.z) + bfhi(a.z) * bfhi(b.z)) + (bflo(a.w) * bflo(b.w) + bfhi(a.w) * bfhi(b.w)); }
; __device__ __forceinline__ void fox_bounds(Frame& F) {
;     ...
;             for (int r = 0; r < 4; ++r) { const int i = qb * 256 + F.lane + 64 * r; const size_t row = (size_t)b * SEQ + i;
;                 const v4u* qp = (const v4u*)(QO + row * DM + 512 + h * 64); const v4u* kp = (const v4u*)(FK + row * 512 + h * 64); float qq = 0.f, qk = 0.f;
; #pragma unroll
;                 for (int d8 = 0; d8 < 8; ++d8) { const v4u qv = qp[d8]; qq += sq8(qv); qk += dot8(qv, kp[d8]); }
	v_and_b32_e32 v19, 0xffff0000, v56
	v_and_b32_e32 v21, 0xffff0000, v57
	v_lshlrev_b32_e32 v18, 16, v56
	v_lshlrev_b32_e32 v20, 16, v57
	v_mul_f32_e32 v14, v19, v19
	v_mul_f32_e32 v15, v21, v21
	v_and_b32_e32 v23, 0xffff0000, v58
	v_fmac_f32_e32 v14, v18, v18
	v_fmac_f32_e32 v15, v20, v20
	v_lshlrev_b32_e32 v22, 16, v58
	v_add_f32_e32 v14, v14, v15
	v_mul_f32_e32 v15, v23, v23
	v_and_b32_e32 v26, 0xffff0000, v59
	v_fmac_f32_e32 v15, v22, v22
	v_lshlrev_b32_e32 v24, 16, v59
	v_add_f32_e32 v14, v15, v14
	v_mul_f32_e32 v15, v26, v26
	v_fmac_f32_e32 v15, v24, v24
	v_add_f32_e32 v14, v15, v14
	v_add_f32_e32 v25, v25, v14
	s_waitcnt vmcnt(8)
	v_lshlrev_b32_e32 v27, 16, v60
	v_and_b32_e32 v14, 0xffff0000, v60
	v_mul_f32_e32 v14, v19, v14
	v_fmac_f32_e32 v14, v18, v27
	v_lshlrev_b32_e32 v18, 16, v61
	v_and_b32_e32 v15, 0xffff0000, v61
	v_mul_f32_e32 v15, v21, v15
	v_fmac_f32_e32 v15, v20, v18
	v_add_f32_e32 v14, v14, v15
	v_lshlrev_b32_e32 v15, 16, v62
	v_and_b32_e32 v16, 0xffff0000, v62
	v_mul_f32_e32 v16, v23, v16
	v_fmac_f32_e32 v16, v22, v15
	v_add_f32_e32 v14, v16, v14
	v_and_b32_e32 v16, 0xffff0000, v63
	v_lshlrev_b32_e32 v15, 16, v63
	v_mul_f32_e32 v16, v26, v16
	v_fmac_f32_e32 v16, v24, v15
	v_add_f32_e32 v14, v16, v14
	v_add_f32_e32 v13, v13, v14
	s_waitcnt vmcnt(7)
	v_and_b32_e32 v19, 0xffff0000, v64
	v_and_b32_e32 v21, 0xffff0000, v65
	v_lshlrev_b32_e32 v18, 16, v64
	v_lshlrev_b32_e32 v20, 16, v65
	v_mul_f32_e32 v14, v19, v19
	v_mul_f32_e32 v15, v21, v21
	v_and_b32_e32 v23, 0xffff0000, v66
	v_fmac_f32_e32 v14, v18, v18
	v_fmac_f32_e32 v15, v20, v20
	v_lshlrev_b32_e32 v22, 16, v66
	v_add_f32_e32 v14, v14, v15
	v_mul_f32_e32 v15, v23, v23
	v_and_b32_e32 v26, 0xffff0000, v67
	v_fmac_f32_e32 v15, v22, v22
	v_lshlrev_b32_e32 v24, 16, v67
	v_add_f32_e32 v14, v15, v14
	v_mul_f32_e32 v15, v26, v26
	v_fmac_f32_e32 v15, v24, v24
	v_add_f32_e32 v14, v15, v14
	v_add_f32_e32 v25, v25, v14
	s_waitcnt vmcnt(6)
	v_lshlrev_b32_e32 v27, 16, v68
	v_and_b32_e32 v14, 0xffff0000, v68
	v_mul_f32_e32 v14, v19, v14
	v_fmac_f32_e32 v14, v18, v27
	v_lshlrev_b32_e32 v18, 16, v69
	v_and_b32_e32 v15, 0xffff0000, v69
	v_mul_f32_e32 v15, v21, v15
	v_fmac_f32_e32 v15, v20, v18
	v_add_f32_e32 v14, v14, v15
	v_lshlrev_b32_e32 v15, 16, v70
	v_and_b32_e32 v16, 0xffff0000, v70
	v_mul_f32_e32 v16, v23, v16
	v_fmac_f32_e32 v16, v22, v15
	v_add_f32_e32 v14, v16, v14
	v_and_b32_e32 v16, 0xffff0000, v71
	v_lshlrev_b32_e32 v15, 16, v71
	v_mul_f32_e32 v16, v26, v16
	v_fmac_f32_e32 v16, v24, v15
	v_add_f32_e32 v14, v16, v14
	v_add_f32_e32 v13, v13, v14
	s_waitcnt vmcnt(5)
	v_and_b32_e32 v19, 0xffff0000, v72
	v_and_b32_e32 v21, 0xffff0000, v73
	v_lshlrev_b32_e32 v18, 16, v72
	v_lshlrev_b32_e32 v20, 16, v73
	v_mul_f32_e32 v14, v19, v19
	v_mul_f32_e32 v15, v21, v21
	v_and_b32_e32 v23, 0xffff0000, v74
	v_fmac_f32_e32 v14, v18, v18
	v_fmac_f32_e32 v15, v20, v20
	v_lshlrev_b32_e32 v22, 16, v74
	v_add_f32_e32 v14, v14, v15
	v_mul_f32_e32 v15, v23, v23
	v_and_b32_e32 v26, 0xffff0000, v75
	v_fmac_f32_e32 v15, v22, v22
	v_lshlrev_b32_e32 v24, 16, v75
	v_add_f32_e32 v14, v15, v14
	v_mul_f32_e32 v15, v26, v26
	v_fmac_f32_e32 v15, v24, v24
	v_add_f32_e32 v14, v15, v14
	v_add_f32_e32 v25, v25, v14
	s_waitcnt vmcnt(4)
	v_lshlrev_b32_e32 v27, 16, v76
	v_and_b32_e32 v14, 0xffff0000, v76
	v_mul_f32_e32 v14, v19, v14
	v_fmac_f32_e32 v14, v18, v27
	v_lshlrev_b32_e32 v18, 16, v77
	v_and_b32_e32 v15, 0xffff0000, v77
	v_mul_f32_e32 v15, v21, v15
	v_fmac_f32_e32 v15, v20, v18
	v_add_f32_e32 v14, v14, v15
	v_lshlrev_b32_e32 v15, 16, v78
	v_and_b32_e32 v16, 0xffff0000, v78
	v_mul_f32_e32 v16, v23, v16
	v_fmac_f32_e32 v16, v22, v15
	v_add_f32_e32 v14, v16, v14
	v_and_b32_e32 v16, 0xffff0000, v79
	v_lshlrev_b32_e32 v15, 16, v79
	v_mul_f32_e32 v16, v26, v16
	v_fmac_f32_e32 v16, v24, v15
	v_add_f32_e32 v14, v16, v14
	v_add_f32_e32 v13, v13, v14
	s_waitcnt vmcnt(3)
	v_and_b32_e32 v19, 0xffff0000, v80
	v_and_b32_e32 v21, 0xffff0000, v81
	v_lshlrev_b32_e32 v18, 16, v80
	v_lshlrev_b32_e32 v20, 16, v81
	v_mul_f32_e32 v14, v19, v19
	v_mul_f32_e32 v15, v21, v21
	v_and_b32_e32 v23, 0xffff0000, v82
	v_fmac_f32_e32 v14, v18, v18
	v_fmac_f32_e32 v15, v20, v20
	v_lshlrev_b32_e32 v22, 16, v82
	v_add_f32_e32 v14, v14, v15
	v_mul_f32_e32 v15, v23, v23
	v_and_b32_e32 v26, 0xffff0000, v83
	v_fmac_f32_e32 v15, v22, v22
	v_lshlrev_b32_e32 v24, 16, v83
	v_add_f32_e32 v14, v15, v14
	v_mul_f32_e32 v15, v26, v26
	v_fmac_f32_e32 v15, v24, v24
	v_add_f32_e32 v14, v15, v14
	v_add_f32_e32 v25, v25, v14
	s_waitcnt vmcnt(2)
; __device__ __forceinline__ float sq8(const v4u w) { const float a0 = bflo(w.x), a1 = bfhi(w.x), a2 = bflo(w.y), a3 = bfhi(w.y), a4 = bflo(w.z), a5 = bfhi(w.z), a6 = bflo(w.w), a7 = bfhi(w.w); return (a0 * a0 + a1 * a1) + (a2 * a2 + a3 * a3) + (a4 * a4 + a5 * a5) + (a6 * a6 + a7 * a7); }
; __device__ __forceinline__ float dot8(const v4u a, const v4u b) { return (bflo(a.x) * bflo(b.x) + bfhi(a.x) * bfhi(b.x)) + (bflo(a.y) * bflo(b.y) + bfhi(a.y) * bfhi(b.y)) + (bflo(a.z) * bflo(b.z) + bfhi(a.z) * bfhi(b.z)) + (bflo(a.w) * bflo(b.w) + bfhi(a.w) * bfhi(b.w)); }
; __device__ __forceinline__ float wave_max(float v) {
; #pragma unroll
;     for (int o = 1; o < 64; o <<= 1) v = fmaxf(v, __shfl_xor(v, o));
;     return v;
; }
; __device__ __forceinline__ void fox_bounds(Frame& F) {
;     ...
;             for (int r = 0; r < 4; ++r) { const int i = qb * 256 + F.lane + 64 * r; const size_t row = (size_t)b * SEQ + i;
;                 const v4u* qp = (const v4u*)(QO + row * DM + 512 + h * 64); const v4u* kp = (const v4u*)(FK + row * 512 + h * 64); float qq = 0.f, qk = 0.f;
; #pragma unroll
;                 for (int d8 = 0; d8 < 8; ++d8) { const v4u qv = qp[d8]; qq += sq8(qv); qk += dot8(qv, kp[d8]); }
;                 q2 = fmaxf(q2, qq); sm = fminf(sm, qk - C2[(size_t)bh * SEQ + i]); }
;             q2 = wave_max(q2); sm = -wave_max(-sm);
;             if (F.lane == 0) { QS[it * 2] = sqrtf(q2); QS[it * 2 + 1] = sm; }
	v_lshlrev_b32_e32 v27, 16, v84
	v_and_b32_e32 v14, 0xffff0000, v84
	v_mul_f32_e32 v14, v19, v14
	v_fmac_f32_e32 v14, v18, v27
	v_lshlrev_b32_e32 v18, 16, v85
	v_and_b32_e32 v15, 0xffff0000, v85
	v_mul_f32_e32 v15, v21, v15
	v_fmac_f32_e32 v15, v20, v18
	v_add_f32_e32 v14, v14, v15
	v_lshlrev_b32_e32 v15, 16, v86
	v_and_b32_e32 v16, 0xffff0000, v86
	v_mul_f32_e32 v16, v23, v16
	v_fmac_f32_e32 v16, v22, v15
	v_add_f32_e32 v14, v16, v14
	v_and_b32_e32 v16, 0xffff0000, v87
	v_lshlrev_b32_e32 v15, 16, v87
	v_mul_f32_e32 v16, v26, v16
	v_fmac_f32_e32 v16, v24, v15
	v_add_f32_e32 v14, v16, v14
	v_add_f32_e32 v13, v13, v14
	s_waitcnt vmcnt(1)
	v_and_b32_e32 v7, 0xffff0000, v88
	v_and_b32_e32 v19, 0xffff0000, v89
	v_lshlrev_b32_e32 v6, 16, v88
	v_lshlrev_b32_e32 v18, 16, v89
	v_mul_f32_e32 v14, v7, v7
	v_mul_f32_e32 v15, v19, v19
	v_and_b32_e32 v21, 0xffff0000, v90
	v_fmac_f32_e32 v14, v6, v6
	v_fmac_f32_e32 v15, v18, v18
	v_lshlrev_b32_e32 v20, 16, v90
	v_add_f32_e32 v14, v14, v15
	v_mul_f32_e32 v15, v21, v21
	v_and_b32_e32 v23, 0xffff0000, v91
	v_fmac_f32_e32 v15, v20, v20
	v_lshlrev_b32_e32 v22, 16, v91
	v_add_f32_e32 v14, v15, v14
	v_mul_f32_e32 v15, v23, v23
	v_fmac_f32_e32 v15, v22, v22
	v_add_f32_e32 v14, v15, v14
	v_add_f32_e32 v24, v25, v14
	s_waitcnt vmcnt(0)
	v_mov_b32_e32 v14, v92
	v_mov_b32_e32 v15, v93
	v_mov_b32_e32 v16, v94
	v_mov_b32_e32 v17, v95
	v_and_b32_e32 v1, 0xffff0000, v14
	v_lshlrev_b32_e32 v0, 16, v14
	v_mul_f32_e32 v1, v7, v1
	v_fmac_f32_e32 v1, v6, v0
	v_and_b32_e32 v6, 0xffff0000, v15
	v_lshlrev_b32_e32 v0, 16, v15
	v_mul_f32_e32 v6, v19, v6
	v_fmac_f32_e32 v6, v18, v0
	v_add_f32_e32 v0, v1, v6
	v_and_b32_e32 v6, 0xffff0000, v16
	v_lshlrev_b32_e32 v1, 16, v16
	v_mul_f32_e32 v6, v21, v6
	v_fmac_f32_e32 v6, v20, v1
	v_add_f32_e32 v0, v6, v0
	v_and_b32_e32 v6, 0xffff0000, v17
	v_lshlrev_b32_e32 v1, 16, v17
	v_mul_f32_e32 v6, v23, v6
	v_fmac_f32_e32 v6, v22, v1
	v_add_f32_e32 v0, v6, v0
	v_add_f32_e32 v1, v13, v0
	v_sub_f32_e32 v1, v1, v2
	v_and_b32_e32 v2, 64, v215
	v_add_u32_e32 v2, 64, v2
	v_cmp_lt_i32_e32 vcc, v3, v2
	v_max3_f32 v0, v12, v9, v24
	v_max3_f32 v1, v10, -v8, -v1
	v_cndmask_b32_e32 v3, v215, v3, vcc
	v_lshlrev_b32_e32 v3, 2, v3
	ds_bpermute_b32 v6, v3, v0
	ds_bpermute_b32 v3, v3, v1
	s_waitcnt lgkmcnt(1)
	v_max_f32_e32 v6, v6, v6
	v_max_f32_e32 v0, v0, v6
	v_xor_b32_e32 v6, 2, v215
	v_cmp_lt_i32_e32 vcc, v6, v2
	s_waitcnt lgkmcnt(0)
	v_max_f32_e32 v3, v3, v3
	v_max_f32_e32 v1, v1, v3
	v_cndmask_b32_e32 v6, v215, v6, vcc
	v_lshlrev_b32_e32 v6, 2, v6
	ds_bpermute_b32 v7, v6, v0
	ds_bpermute_b32 v3, v6, v1
	s_waitcnt lgkmcnt(1)
	v_max_f32_e32 v7, v7, v7
	v_max_f32_e32 v0, v0, v7
	v_xor_b32_e32 v7, 4, v215
	v_cmp_lt_i32_e32 vcc, v7, v2
	s_waitcnt lgkmcnt(0)
	v_max_f32_e32 v3, v3, v3
	v_max_f32_e32 v1, v1, v3
	v_cndmask_b32_e32 v7, v215, v7, vcc
	v_lshlrev_b32_e32 v7, 2, v7
	ds_bpermute_b32 v9, v7, v0
	ds_bpermute_b32 v3, v7, v1
	s_waitcnt lgkmcnt(1)
	v_max_f32_e32 v9, v9, v9
	v_max_f32_e32 v0, v0, v9
	v_xor_b32_e32 v9, 8, v215
	v_cmp_lt_i32_e32 vcc, v9, v2
	s_waitcnt lgkmcnt(0)
	v_max_f32_e32 v3, v3, v3
	v_max_f32_e32 v1, v1, v3
	v_cndmask_b32_e32 v9, v215, v9, vcc
	v_lshlrev_b32_e32 v9, 2, v9
	ds_bpermute_b32 v12, v9, v0
	ds_bpermute_b32 v3, v9, v1
	s_waitcnt lgkmcnt(1)
	v_max_f32_e32 v12, v12, v12
	v_max_f32_e32 v0, v0, v12
	v_xor_b32_e32 v12, 16, v215
	v_cmp_lt_i32_e32 vcc, v12, v2
	s_waitcnt lgkmcnt(0)
	v_max_f32_e32 v3, v3, v3
	v_max_f32_e32 v1, v1, v3
	v_cndmask_b32_e32 v12, v215, v12, vcc
	v_lshlrev_b32_e32 v12, 2, v12
	ds_bpermute_b32 v13, v12, v0
	ds_bpermute_b32 v3, v12, v1
	s_waitcnt lgkmcnt(1)
	v_max_f32_e32 v13, v13, v13
	v_max_f32_e32 v0, v0, v13
	v_xor_b32_e32 v13, 32, v215
	v_cmp_lt_i32_e32 vcc, v13, v2
	s_waitcnt lgkmcnt(0)
	v_max_f32_e32 v3, v3, v3
	v_max_f32_e32 v1, v1, v3
	v_cndmask_b32_e32 v2, v215, v13, vcc
	v_lshlrev_b32_e32 v13, 2, v2
	ds_bpermute_b32 v2, v13, v0
	ds_bpermute_b32 v3, v13, v1
	s_and_saveexec_b64 s[24:25], s[4:5]
	s_cbranch_execz .LBB0_610
	s_waitcnt lgkmcnt(1)
	v_max_f32_e32 v2, v2, v2
	v_max_f32_e32 v0, v0, v0
	v_max_f32_e32 v0, v0, v2
	v_mul_f32_e32 v2, 0x4f800000, v0
	v_cmp_gt_f32_e32 vcc, s89, v0
	s_mov_b32 s19, s69
	s_lshl_b64 s[6:7], s[18:19], 2
	v_cndmask_b32_e32 v0, v0, v2, vcc
	v_sqrt_f32_e32 v2, v0
	s_add_u32 s38, s27, s6
	s_addc_u32 s39, s28, s7
	v_max_f32_e64 v1, -v1, -v1
	v_add_u32_e32 v6, -1, v2
	v_fma_f32 v7, -v6, v2, v0
	v_cmp_ge_f32_e64 s[6:7], 0, v7
	v_add_u32_e32 v7, 1, v2
	s_nop 0
	v_cndmask_b32_e64 v6, v2, v6, s[6:7]
	v_fma_f32 v2, -v7, v2, v0
	v_cmp_lt_f32_e64 s[6:7], 0, v2
	s_nop 1
	v_cndmask_b32_e64 v2, v6, v7, s[6:7]
	v_mul_f32_e32 v6, 0x37800000, v2
	v_cndmask_b32_e32 v2, v2, v6, vcc
	v_cmp_class_f32_e32 vcc, v0, v213
	s_nop 1
	v_cndmask_b32_e32 v0, v2, v0, vcc
	s_waitcnt lgkmcnt(0)
	v_max_f32_e64 v2, -v3, -v3
	v_min_f32_e32 v1, v1, v2
	v_mov_b64_e32 v[2:3], s[38:39]
	flat_store_dwordx2 v[2:3], v[0:1]

; __device__ __forceinline__ float bflo(unsigned w) { return __uint_as_float(w << 16); }
; __device__ __forceinline__ float bfhi(unsigned w) { return __uint_as_float(w & 0xffff0000u); }
; __device__ __forceinline__ float sq8(const v4u w) { const float a0 = bflo(w.x), a1 = bfhi(w.x), a2 = bflo(w.y), a3 = bfhi(w.y), a4 = bflo(w.z), a5 = bfhi(w.z), a6 = bflo(w.w), a7 = bfhi(w.w); return (a0 * a0 + a1 * a1) + (a2 * a2 + a3 * a3) + (a4 * a4 + a5 * a5) + (a6 * a6 + a7 * a7); }
; __device__ __forceinline__ void fox_bounds(Frame& F) {
;     ...
;         if (item < 2048) { const int bh = item >> 7, t = item & 127, b = bh >> 3, h = bh & 7; const v4u* kp = (const v4u*)(FK + ((size_t)b * SEQ + t * 64 + F.lane) * 512 + h * 64);
;             float k2 = 0.f;
; #pragma unroll
;             for (int d8 = 0; d8 < 8; ++d8) k2 += sq8(kp[d8]);
;             k2 = wave_max(k2); if (F.lane == 0) KMAX[item] = sqrtf(k2);
.LBB0_611:
	s_andn2_b64 vcc, exec, s[6:7]
	s_cbranch_vccnz .LBB0_606
	s_ashr_i32 s6, s15, 10
	s_ashr_i32 s7, s6, 31
	s_lshl_b64 s[6:7], s[6:7], 13
	s_and_b32 s2, s35, 0x1fc0
	s_or_b32 s2, s6, s2
	s_waitcnt lgkmcnt(0)
	v_mov_b32_e32 v1, s7
	v_or_b32_e32 v0, s2, v4
	v_lshlrev_b64 v[0:1], 10, v[0:1]
	v_lshl_add_u64 v[0:1], s[16:17], 0, v[0:1]
	s_and_b32 s68, s15, 0x380
	v_lshl_add_u64 v[0:1], v[0:1], 0, s[68:69]
	global_load_dwordx4 v[32:35], v[0:1], off
	global_load_dwordx4 v[36:39], v[0:1], off offset:16
	global_load_dwordx4 v[40:43], v[0:1], off offset:32
	global_load_dwordx4 v[44:47], v[0:1], off offset:48
	global_load_dwordx4 v[48:51], v[0:1], off offset:64
	global_load_dwordx4 v[52:55], v[0:1], off offset:80
	global_load_dwordx4 v[56:59], v[0:1], off offset:96
	global_load_dwordx4 v[60:63], v[0:1], off offset:112
	s_waitcnt vmcnt(7)
	v_and_b32_e32 v3, 0xffff0000, v32
	v_lshlrev_b32_e32 v2, 16, v32
	v_lshlrev_b32_e32 v6, 16, v33
	v_and_b32_e32 v7, 0xffff0000, v33
	v_mul_f32_e32 v3, v3, v3
	v_fmac_f32_e32 v3, v2, v2
	v_mul_f32_e32 v2, v7, v7
	v_lshlrev_b32_e32 v10, 16, v34
	v_and_b32_e32 v8, 0xffff0000, v34
	v_fmac_f32_e32 v2, v6, v6
	v_add_f32_e32 v2, v3, v2
	v_mul_f32_e32 v3, v8, v8
	v_lshlrev_b32_e32 v11, 16, v35
	v_and_b32_e32 v9, 0xffff0000, v35
	v_fmac_f32_e32 v3, v10, v10
	v_add_f32_e32 v2, v3, v2
	v_mul_f32_e32 v3, v9, v9
	v_fmac_f32_e32 v3, v11, v11
	v_add_f32_e32 v2, v3, v2
	s_waitcnt vmcnt(6)
	v_lshlrev_b32_e32 v3, 16, v36
	v_and_b32_e32 v6, 0xffff0000, v36
	v_lshlrev_b32_e32 v10, 16, v37
	v_and_b32_e32 v7, 0xffff0000, v37
	v_mul_f32_e32 v6, v6, v6
	v_fmac_f32_e32 v6, v3, v3
	v_mul_f32_e32 v3, v7, v7
	v_lshlrev_b32_e32 v11, 16, v38
	v_and_b32_e32 v8, 0xffff0000, v38
	v_fmac_f32_e32 v3, v10, v10
	v_add_f32_e32 v3, v6, v3
	v_mul_f32_e32 v6, v8, v8
	v_lshlrev_b32_e32 v12, 16, v39
	v_and_b32_e32 v9, 0xffff0000, v39
	v_fmac_f32_e32 v6, v11, v11
	v_add_f32_e32 v3, v6, v3
	v_mul_f32_e32 v6, v9, v9
	v_fmac_f32_e32 v6, v12, v12
	v_add_f32_e32 v3, v6, v3
	v_add_f32_e32 v2, v2, v3
	s_waitcnt vmcnt(5)
	v_lshlrev_b32_e32 v3, 16, v40
	v_and_b32_e32 v6, 0xffff0000, v40
	v_lshlrev_b32_e32 v10, 16, v41
	v_and_b32_e32 v7, 0xffff0000, v41
	v_mul_f32_e32 v6, v6, v6
	v_fmac_f32_e32 v6, v3, v3
	v_mul_f32_e32 v3, v7, v7
	v_lshlrev_b32_e32 v11, 16, v42
	v_and_b32_e32 v8, 0xffff0000, v42
	v_fmac_f32_e32 v3, v10, v10
	v_add_f32_e32 v3, v6, v3
	v_mul_f32_e32 v6, v8, v8
	v_lshlrev_b32_e32 v12, 16, v43
	v_and_b32_e32 v9, 0xffff0000, v43
	v_fmac_f32_e32 v6, v11, v11
	v_add_f32_e32 v3, v6, v3
	v_mul_f32_e32 v6, v9, v9
	v_fmac_f32_e32 v6, v12, v12
	v_add_f32_e32 v3, v6, v3
	v_add_f32_e32 v2, v2, v3
	s_waitcnt vmcnt(4)
	v_lshlrev_b32_e32 v3, 16, v44
	v_and_b32_e32 v6, 0xffff0000, v44
	v_lshlrev_b32_e32 v10, 16, v45
	v_and_b32_e32 v7, 0xffff0000, v45
	v_mul_f32_e32 v6, v6, v6
	v_fmac_f32_e32 v6, v3, v3
	v_mul_f32_e32 v3, v7, v7
	v_lshlrev_b32_e32 v11, 16, v46
	v_and_b32_e32 v8, 0xffff0000, v46
	v_fmac_f32_e32 v3, v10, v10
	v_add_f32_e32 v3, v6, v3
	v_mul_f32_e32 v6, v8, v8
	v_lshlrev_b32_e32 v12, 16, v47
	v_and_b32_e32 v9, 0xffff0000, v47
	v_fmac_f32_e32 v6, v11, v11
	v_add_f32_e32 v3, v6, v3
	v_mul_f32_e32 v6, v9, v9
	v_fmac_f32_e32 v6, v12, v12
	v_add_f32_e32 v3, v6, v3
	v_add_f32_e32 v2, v2, v3
	s_waitcnt vmcnt(3)
	v_lshlrev_b32_e32 v3, 16, v48
	v_and_b32_e32 v6, 0xffff0000, v48
	v_lshlrev_b32_e32 v10, 16, v49
	v_and_b32_e32 v7, 0xffff0000, v49
	v_mul_f32_e32 v6, v6, v6
	v_fmac_f32_e32 v6, v3, v3
	v_mul_f32_e32 v3, v7, v7
	v_lshlrev_b32_e32 v11, 16, v50
	v_and_b32_e32 v8, 0xffff0000, v50
	v_fmac_f32_e32 v3, v10, v10
	v_add_f32_e32 v3, v6, v3
	v_mul_f32_e32 v6, v8, v8
	v_lshlrev_b32_e32 v12, 16, v51
	v_and_b32_e32 v9, 0xffff0000, v51
	v_fmac_f32_e32 v6, v11, v11
	v_add_f32_e32 v3, v6, v3
	v_mul_f32_e32 v6, v9, v9
	v_fmac_f32_e32 v6, v12, v12
	v_add_f32_e32 v3, v6, v3
	v_add_f32_e32 v2, v2, v3
	s_waitcnt vmcnt(2)
; __device__ __forceinline__ float sq8(const v4u w) { const float a0 = bflo(w.x), a1 = bfhi(w.x), a2 = bflo(w.y), a3 = bfhi(w.y), a4 = bflo(w.z), a5 = bfhi(w.z), a6 = bflo(w.w), a7 = bfhi(w.w); return (a0 * a0 + a1 * a1) + (a2 * a2 + a3 * a3) + (a4 * a4 + a5 * a5) + (a6 * a6 + a7 * a7); }
; __device__ __forceinline__ float wave_max(float v) {
; #pragma unroll
;     for (int o = 1; o < 64; o <<= 1) v = fmaxf(v, __shfl_xor(v, o));
;     return v;
; }
; __device__ __forceinline__ void fox_bounds(Frame& F) {
;     ...
;             for (int d8 = 0; d8 < 8; ++d8) k2 += sq8(kp[d8]);
;             k2 = wave_max(k2); if (F.lane == 0) KMAX[item] = sqrtf(k2);
	v_lshlrev_b32_e32 v3, 16, v52
	v_and_b32_e32 v6, 0xffff0000, v52
	v_lshlrev_b32_e32 v10, 16, v53
	v_and_b32_e32 v7, 0xffff0000, v53
	v_mul_f32_e32 v6, v6, v6
	v_fmac_f32_e32 v6, v3, v3
	v_mul_f32_e32 v3, v7, v7
	v_lshlrev_b32_e32 v11, 16, v54
	v_and_b32_e32 v8, 0xffff0000, v54
	v_fmac_f32_e32 v3, v10, v10
	v_add_f32_e32 v3, v6, v3
	v_mul_f32_e32 v6, v8, v8
	v_lshlrev_b32_e32 v12, 16, v55
	v_and_b32_e32 v9, 0xffff0000, v55
	v_fmac_f32_e32 v6, v11, v11
	v_add_f32_e32 v3, v6, v3
	v_mul_f32_e32 v6, v9, v9
	v_fmac_f32_e32 v6, v12, v12
	v_add_f32_e32 v3, v6, v3
	v_add_f32_e32 v2, v2, v3
	s_waitcnt vmcnt(1)
	v_lshlrev_b32_e32 v3, 16, v56
	v_and_b32_e32 v6, 0xffff0000, v56
	v_lshlrev_b32_e32 v10, 16, v57
	v_and_b32_e32 v7, 0xffff0000, v57
	v_mul_f32_e32 v6, v6, v6
	v_fmac_f32_e32 v6, v3, v3
	v_mul_f32_e32 v3, v7, v7
	v_lshlrev_b32_e32 v11, 16, v58
	v_and_b32_e32 v8, 0xffff0000, v58
	v_fmac_f32_e32 v3, v10, v10
	v_add_f32_e32 v3, v6, v3
	v_mul_f32_e32 v6, v8, v8
	v_lshlrev_b32_e32 v12, 16, v59
	v_and_b32_e32 v9, 0xffff0000, v59
	v_fmac_f32_e32 v6, v11, v11
	v_add_f32_e32 v3, v6, v3
	v_mul_f32_e32 v6, v9, v9
	v_fmac_f32_e32 v6, v12, v12
	v_add_f32_e32 v3, v6, v3
	v_add_f32_e32 v6, v2, v3
	s_waitcnt vmcnt(0)
	v_mov_b32_e32 v0, v60
	v_mov_b32_e32 v1, v61
	v_mov_b32_e32 v2, v62
	v_mov_b32_e32 v3, v63
	v_lshlrev_b32_e32 v7, 16, v0
	v_and_b32_e32 v0, 0xffff0000, v0
	v_lshlrev_b32_e32 v8, 16, v1
	v_and_b32_e32 v1, 0xffff0000, v1
	v_mul_f32_e32 v0, v0, v0
	v_mul_f32_e32 v1, v1, v1
	v_lshlrev_b32_e32 v9, 16, v2
	v_and_b32_e32 v2, 0xffff0000, v2
	v_fmac_f32_e32 v0, v7, v7
	v_fmac_f32_e32 v1, v8, v8
	v_add_f32_e32 v0, v0, v1
	v_mul_f32_e32 v1, v2, v2
	v_lshlrev_b32_e32 v10, 16, v3
	v_and_b32_e32 v3, 0xffff0000, v3
	v_fmac_f32_e32 v1, v9, v9
	v_add_f32_e32 v0, v1, v0
	v_mul_f32_e32 v1, v3, v3
	v_fmac_f32_e32 v1, v10, v10
	v_add_f32_e32 v0, v1, v0
	v_and_b32_e32 v1, 64, v215
	v_add_u32_e32 v1, 64, v1
	v_xor_b32_e32 v2, 1, v215
	v_cmp_lt_i32_e32 vcc, v2, v1
	v_add_f32_e32 v0, v6, v0
	s_nop 0
	v_cndmask_b32_e32 v2, v215, v2, vcc
	v_lshlrev_b32_e32 v2, 2, v2
	ds_bpermute_b32 v2, v2, v0
	s_waitcnt lgkmcnt(0)
	v_max_f32_e32 v2, v2, v2
	v_max_f32_e32 v0, v0, v2
	v_xor_b32_e32 v2, 2, v215
	v_cmp_lt_i32_e32 vcc, v2, v1
	s_nop 1
	v_cndmask_b32_e32 v2, v215, v2, vcc
	v_lshlrev_b32_e32 v2, 2, v2
	ds_bpermute_b32 v2, v2, v0
	s_waitcnt lgkmcnt(0)
	v_max_f32_e32 v2, v2, v2
	v_max_f32_e32 v0, v0, v2
	v_xor_b32_e32 v2, 4, v215
	v_cmp_lt_i32_e32 vcc, v2, v1
	s_nop 1
	v_cndmask_b32_e32 v2, v215, v2, vcc
	v_lshlrev_b32_e32 v2, 2, v2
	ds_bpermute_b32 v2, v2, v0
	s_waitcnt lgkmcnt(0)
	v_max_f32_e32 v2, v2, v2
	v_max_f32_e32 v0, v0, v2
	v_xor_b32_e32 v2, 8, v215
	v_cmp_lt_i32_e32 vcc, v2, v1
	s_nop 1
	v_cndmask_b32_e32 v2, v215, v2, vcc
	v_lshlrev_b32_e32 v2, 2, v2
	ds_bpermute_b32 v2, v2, v0
	s_waitcnt lgkmcnt(0)
	v_max_f32_e32 v2, v2, v2
	v_max_f32_e32 v0, v0, v2
	v_xor_b32_e32 v2, 16, v215
	v_cmp_lt_i32_e32 vcc, v2, v1
	s_nop 1
	v_cndmask_b32_e32 v2, v215, v2, vcc
	v_lshlrev_b32_e32 v2, 2, v2
	ds_bpermute_b32 v2, v2, v0
	s_waitcnt lgkmcnt(0)
	v_max_f32_e32 v2, v2, v2
	v_max_f32_e32 v0, v0, v2
	v_xor_b32_e32 v2, 32, v215
	v_cmp_lt_i32_e32 vcc, v2, v1
	s_nop 1
	v_cndmask_b32_e32 v1, v215, v2, vcc
	v_lshlrev_b32_e32 v1, 2, v1
	ds_bpermute_b32 v1, v1, v0
	s_and_saveexec_b64 s[24:25], s[4:5]
	s_cbranch_execz .LBB0_605
	s_waitcnt lgkmcnt(0)
	v_max_f32_e32 v1, v1, v1
	v_max_f32_e32 v0, v0, v0
	v_max_f32_e32 v0, v0, v1
	v_mul_f32_e32 v1, 0x4f800000, v0
	v_cmp_gt_f32_e32 vcc, s89, v0
	s_nop 1
	v_cndmask_b32_e32 v0, v0, v1, vcc
	v_sqrt_f32_e32 v1, v0
	s_nop 0
	v_add_u32_e32 v2, -1, v1
	v_fma_f32 v3, -v2, v1, v0
	v_cmp_ge_f32_e64 s[6:7], 0, v3
	v_add_u32_e32 v3, 1, v1
	s_nop 0
	v_cndmask_b32_e64 v2, v1, v2, s[6:7]
	v_fma_f32 v1, -v3, v1, v0
	v_cmp_lt_f32_e64 s[6:7], 0, v1
	s_nop 1
	v_cndmask_b32_e64 v1, v2, v3, s[6:7]
	v_mul_f32_e32 v2, 0x37800000, v1
	v_cndmask_b32_e32 v1, v1, v2, vcc
	v_cmp_class_f32_e32 vcc, v0, v213
	s_nop 1
	v_cndmask_b32_e32 v2, v1, v0, vcc
	v_mov_b64_e32 v[0:1], s[20:21]
	flat_store_dword v[0:1], v2
	s_branch .LBB0_605
